# EpiQKV epilogue regenerated (wide stores, fewer LDS round trips) + XCD-aligned QKV unit mapping, on top of v26
# speedup vs baseline: 1.0049x; 1.0049x over previous
;     __host__ __device__ bool next(int i, Unit& u) const {
;         const long L = (long)i * G + c; if (L >= nwg) return false;
;         int wgid = (int)L; { const int q = nwg / NXCD, r = nwg % NXCD, xcd = wgid % NXCD, off = wgid / NXCD; wgid = (xcd < r ? xcd * (q + 1) : r * (q + 1) + (xcd - r) * q) + off; }
;         const int nig = WGM * nN, gid = wgid / nig, fm = gid * WGM, gsz = (nM - fm) < WGM ? (nM - fm) : WGM;
;         u.pm = fm + ((wgid % nig) % gsz); u.pn = (wgid % nig) / gsz; return true;
.LBB0_557:
	s_andn2_b64 vcc, exec, s[0:1]
	s_cbranch_vccnz .LBB0_1031
	v_mov_b32_e32 v186, v215
	s_mov_b32 s87, s84
	s_mov_b32 s31, s82
	s_cmpk_lt_i32 s87, 0x210
	v_readfirstlane_b32 s4, v186
	s_mov_b64 s[0:1], s[94:95]
	s_cselect_b64 s[2:3], -1, 0
	s_cmpk_gt_i32 s87, 0x20f
	s_cbranch_scc1 .LBB0_560
	s_ashr_i32 s5, s87, 31
	s_lshr_b32 s5, s5, 29
	s_add_i32 s5, s87, s5
	s_waitcnt lgkmcnt(0)
	s_ashr_i32 s6, s5, 3
	s_and_b32 s5, s5, -8
	s_sub_i32 s5, s87, s5
	s_cmp_lt_i32 s5, 0
	s_movk_i32 s7, 0x43
	s_cselect_b32 s7, s7, 0x42
	s_lshl_b32 s7, s5, 6
	s_add_i32 s7, s7, s6
	s_sub_i32 s8, s6, 64
	s_lshl_b32 s8, s8, 3
	s_add_i32 s8, s8, s5
	s_addk_i32 s8, 0x200
	s_cmp_lt_i32 s6, 64
	s_cselect_b32 s5, s7, s8
	s_ashr_i32 s6, s5, 31
	s_lshr_b32 s6, s6, 26
	s_add_i32 s6, s5, s6
	s_ashr_i32 s7, s6, 6
	s_lshl_b32 s8, s7, 3
	s_sub_i32 s7, 0x42, s8
	s_min_u32 s12, s7, 8
	s_andn2_b32 s6, s6, 63
	s_sub_i32 s5, s5, s6
	s_waitcnt vmcnt(0)
	v_cvt_f32_ubyte0_e32 v1, s12
	v_cvt_f32_i32_e32 v0, s5
	v_rcp_iflag_f32_e32 v2, v1
	s_ashr_i32 s6, s5, 30
	s_or_b32 s13, s6, 1
	v_mul_f32_e32 v2, v0, v2
	v_trunc_f32_e32 v2, v2
	v_fma_f32 v0, -v2, v1, v0
	v_cvt_i32_f32_e32 v2, v2
	v_cmp_ge_f32_e64 s[6:7], |v0|, v1
	s_and_b64 s[6:7], s[6:7], exec
	s_cselect_b32 s6, s13, 0
	v_readfirstlane_b32 s7, v2
	s_add_i32 s6, s7, s6
	s_sext_i32_i8 s46, s6
	s_mul_i32 s6, s6, s12
	s_sub_i32 s5, s5, s6
	s_sext_i32_i8 s5, s5
	s_add_i32 s42, s8, s5

;     __host__ __device__ bool next(int i, Unit& u) const {
;         const long L = (long)i * G + c; if (L >= nwg) return false;
;         int wgid = (int)L; { const int q = nwg / NXCD, r = nwg % NXCD, xcd = wgid % NXCD, off = wgid / NXCD; wgid = (xcd < r ? xcd * (q + 1) : r * (q + 1) + (xcd - r) * q) + off; }
;         const int nig = WGM * nN, gid = wgid / nig, fm = gid * WGM, gsz = (nM - fm) < WGM ? (nM - fm) : WGM;
;         u.pm = fm + ((wgid % nig) % gsz); u.pn = (wgid % nig) / gsz; return true;
; template <class Epi, class Sched>
; __device__ __forceinline__ void gemm_phase(PG8_LAS unsigned char* lds, const Gemm g, const Sched& S, const Epi& E, const int tid) {
;     ...
;         const bool has_next = S.next(ui + 1, nxt);
.LBB0_566:
	s_add_i32 s57, s57, 1
	s_mul_i32 s8, s57, s5
	s_mul_hi_u32 s16, s57, s31
	s_add_i32 s16, s16, s8
	s_mul_i32 s8, s57, s31
	s_add_u32 s60, s8, s87
	s_addc_u32 s61, s16, s86
	v_mov_b64_e32 v[0:1], 0x210
	v_cmp_lt_i64_e64 s[40:41], s[60:61], v[0:1]
	v_mov_b64_e32 v[0:1], 0x20f
	v_cmp_gt_i64_e32 vcc, s[60:61], v[0:1]
	s_cbranch_vccnz .LBB0_568
	s_ashr_i32 s8, s60, 31
	s_lshr_b32 s8, s8, 29
	s_add_i32 s8, s60, s8
	s_ashr_i32 s16, s8, 3
	s_and_b32 s8, s8, -8
	s_sub_i32 s8, s60, s8
	s_cmp_lt_i32 s8, 0
	s_movk_i32 s17, 0x43
	s_cselect_b32 s17, s17, 0x42
	s_lshl_b32 s17, s8, 6
	s_add_i32 s17, s17, s16
	s_sub_i32 s20, s16, 64
	s_lshl_b32 s20, s20, 3
	s_add_i32 s20, s20, s8
	s_addk_i32 s20, 0x200
	s_cmp_lt_i32 s16, 64
	s_cselect_b32 s8, s17, s20
	s_ashr_i32 s16, s8, 31
	s_lshr_b32 s16, s16, 26
	s_add_i32 s16, s8, s16
	s_ashr_i32 s17, s16, 6
	s_lshl_b32 s17, s17, 3
	s_sub_i32 s20, 0x42, s17
	s_min_i32 s20, s20, 8
	s_abs_i32 s21, s20
	v_cvt_f32_u32_e32 v0, s21
	s_sub_i32 s23, 0, s21
	s_andn2_b32 s16, s16, 63
	s_sub_i32 s8, s8, s16
	v_rcp_iflag_f32_e32 v0, v0
	s_abs_i32 s16, s8
	s_xor_b32 s22, s8, s20
	s_ashr_i32 s22, s22, 31
	v_mul_f32_e32 v0, 0x4f7ffffe, v0
	v_cvt_u32_f32_e32 v0, v0
	s_nop 0
	v_readfirstlane_b32 s30, v0
	s_mul_i32 s23, s23, s30
	s_mul_hi_u32 s23, s30, s23
	s_add_i32 s30, s30, s23
	s_mul_hi_u32 s23, s16, s30
	s_mul_i32 s30, s23, s21
	s_sub_i32 s16, s16, s30
	s_add_i32 s33, s23, 1
	s_sub_i32 s30, s16, s21
	s_cmp_ge_u32 s16, s21
	s_cselect_b32 s23, s33, s23
	s_cselect_b32 s16, s30, s16
	s_add_i32 s30, s23, 1
	s_cmp_ge_u32 s16, s21
	s_cselect_b32 s16, s30, s23
	s_xor_b32 s16, s16, s22
	s_sub_i32 s34, s16, s22
	s_mul_i32 s16, s34, s20
	s_sub_i32 s8, s8, s16
	s_add_i32 s64, s17, s8

;     __device__ __forceinline__ void operator()(f32x4 (&acc)[2][2][4][2], const Unit& u, int wr, int wc, int fr, int fq) const {
;         asm volatile("" : "+v"(fr), "+v"(fq));
;         const int rowt = u.pm * BM, b = rowt >= MLAT ? 2 : (rowt >> 13); const bool is_lat = rowt < MLAT;
;         if (!is_lat && u.pn < 4) return;
;         const int col0 = u.pn * BM + wc * 32 + 8 * fq;
;         const bool qk = u.pn < 6;
;         {   f32x4 bv[2][2];
; #pragma unroll
;             for (int bj = 0; bj < 2; ++bj)
; #pragma unroll
;                 for (int n = 0; n < 2; ++n) bv[bj][n] = *(const f32x4*)(bias + (size_t)b * 2048 + col0 + bj * HALF + 4 * n);
;             float rsv[2][4];
;             { f32x4 pq[2][4];
; #pragma unroll
;               for (int ai = 0; ai < 2; ++ai)
; #pragma unroll
;                   for (int m = 0; m < 4; ++m) pq[ai][m] = *(const f32x4*)(ssq + (size_t)(rowt + wr * 64 + fr + ai * HALF + m * 16) * 16 + 4 * fq);
; #pragma unroll
;               for (int ai = 0; ai < 2; ++ai)
; #pragma unroll
;                   for (int m = 0; m < 4; ++m) { float t = (pq[ai][m][0] + pq[ai][m][1]) + (pq[ai][m][2] + pq[ai][m][3]); t += __shfl_xor(t, 16); t += __shfl_xor(t, 32);
;                       rsv[ai][m] = rsqrtf(t * (1.f / DM) + EPS); } }
.LBB0_572:
	s_cmp_gt_i32 s42, 63
	s_cselect_b32 s16, 1, 0
	s_cmp_lt_i32 s46, 4
	s_cselect_b32 s17, 1, 0
	s_and_b32 s8, s16, s17
	s_cmp_lg_u32 s8, 0
	s_cbranch_scc1 .Lqkv_epi_end
	s_load_dwordx2 s[20:21], s[0:1], 0xb8
	s_mov_b32 s35, s46
	s_load_dwordx4 s[44:47], s[0:1], 0x68
	v_and_b32_e32 v199, 63, v215
	v_lshrrev_b32_e32 v200, 6, v215
	v_and_b32_e32 v201, 15, v199
	v_lshrrev_b32_e32 v202, 4, v199
	v_readfirstlane_b32 s58, v200
	s_nop 3
	s_and_b32 s59, s58, 3
	s_lshr_b32 s58, s58, 2
	s_lshl_b32 s65, s58, 6
	v_add_u32_e32 v203, s65, v201
	s_min_i32 s8, s42, 64
	s_ashr_i32 s8, s8, 5
	s_lshl_b32 s8, s8, 13
	s_waitcnt lgkmcnt(0)
	s_add_u32 s22, s20, 0xb0000
	s_addc_u32 s23, s21, 0
	s_add_u32 s22, s22, s8
	s_addc_u32 s23, s23, 0
	s_lshl_b32 s8, s35, 8
	s_lshl_b32 s72, s59, 5
	s_or_b32 s8, s8, s72
	v_lshlrev_b32_e32 v199, 3, v202
	v_or_b32_e32 v199, s8, v199
	v_lshlrev_b32_e32 v200, 2, v199
	global_load_dwordx4 v[144:147], v200, s[22:23] offset:0
	global_load_dwordx4 v[148:151], v200, s[22:23] offset:16
	global_load_dwordx4 v[152:155], v200, s[22:23] offset:512
	global_load_dwordx4 v[156:159], v200, s[22:23] offset:528
	s_add_u32 s72, s20, 0x14000000
	s_addc_u32 s73, s21, 0
	v_lshl_add_u32 v192, s42, 8, v203
	v_mov_b32_e32 v193, 0
	v_lshlrev_b64 v[194:195], 6, v[192:193]
	v_lshlrev_b32_e32 v200, 4, v202
	v_or_b32_e32 v194, v194, v200
	v_lshl_add_u64 v[194:195], s[72:73], 0, v[194:195]
	s_mov_b64 s[72:73], 0x2000
	v_lshl_add_u64 v[196:197], v[194:195], 0, s[72:73]
	global_load_dwordx4 v[68:71], v[194:195], off offset:0
	global_load_dwordx4 v[76:79], v[194:195], off offset:1024
	global_load_dwordx4 v[80:83], v[194:195], off offset:2048
	global_load_dwordx4 v[84:87], v[194:195], off offset:3072
	global_load_dwordx4 v[160:163], v[196:197], off offset:0
	global_load_dwordx4 v[174:177], v[196:197], off offset:1024
	global_load_dwordx4 v[178:181], v[196:197], off offset:2048
	global_load_dwordx4 v[182:185], v[196:197], off offset:3072
	s_waitcnt vmcnt(0)
	v_add_f32_e32 v68, v68, v69
	v_add_f32_e32 v70, v70, v71
	v_add_f32_e32 v76, v76, v77
	v_add_f32_e32 v78, v78, v79
	v_add_f32_e32 v80, v80, v81
	v_add_f32_e32 v82, v82, v83
	v_add_f32_e32 v84, v84, v85
	v_add_f32_e32 v86, v86, v87
	v_add_f32_e32 v160, v160, v161
	v_add_f32_e32 v162, v162, v163
	v_add_f32_e32 v174, v174, v175
	v_add_f32_e32 v176, v176, v177
	v_add_f32_e32 v178, v178, v179
	v_add_f32_e32 v180, v180, v181
	v_add_f32_e32 v182, v182, v183
	v_add_f32_e32 v184, v184, v185
	v_add_f32_e32 v191, v68, v70
	v_add_f32_e32 v192, v76, v78
	v_add_f32_e32 v193, v80, v82
	v_add_f32_e32 v194, v84, v86
	v_add_f32_e32 v195, v160, v162
	v_add_f32_e32 v196, v174, v176
	v_add_f32_e32 v197, v178, v180
	v_add_f32_e32 v198, v182, v184
	v_mov_b32_e32 v68, v191
	v_mov_b32_e32 v69, v191
	v_mov_b32_e32 v76, v192
	v_mov_b32_e32 v77, v192
	v_mov_b32_e32 v80, v193
	v_mov_b32_e32 v81, v193
	v_mov_b32_e32 v84, v194
	v_mov_b32_e32 v85, v194
	v_mov_b32_e32 v160, v195
	v_mov_b32_e32 v161, v195
	v_mov_b32_e32 v174, v196
	v_mov_b32_e32 v175, v196
	v_mov_b32_e32 v178, v197
	v_mov_b32_e32 v179, v197
	v_mov_b32_e32 v182, v198
	v_mov_b32_e32 v183, v198
	s_nop 1
	v_permlane16_swap_b32_e32 v68, v69
	v_permlane16_swap_b32_e32 v76, v77
	v_permlane16_swap_b32_e32 v80, v81
	v_permlane16_swap_b32_e32 v84, v85
	v_permlane16_swap_b32_e32 v160, v161
	v_permlane16_swap_b32_e32 v174, v175
	v_permlane16_swap_b32_e32 v178, v179
	v_permlane16_swap_b32_e32 v182, v183
	v_add_f32_e32 v191, v68, v69
	v_add_f32_e32 v192, v76, v77
	v_add_f32_e32 v193, v80, v81
	v_add_f32_e32 v194, v84, v85
	v_add_f32_e32 v195, v160, v161
	v_add_f32_e32 v196, v174, v175
	v_add_f32_e32 v197, v178, v179
	v_add_f32_e32 v198, v182, v183
	v_mov_b32_e32 v68, v191
	v_mov_b32_e32 v69, v191
	v_mov_b32_e32 v76, v192
	v_mov_b32_e32 v77, v192
	v_mov_b32_e32 v80, v193
	v_mov_b32_e32 v81, v193
	v_mov_b32_e32 v84, v194
	v_mov_b32_e32 v85, v194
	v_mov_b32_e32 v160, v195
	v_mov_b32_e32 v161, v195
	v_mov_b32_e32 v174, v196
	v_mov_b32_e32 v175, v196
	v_mov_b32_e32 v178, v197
	v_mov_b32_e32 v179, v197
	v_mov_b32_e32 v182, v198
	v_mov_b32_e32 v183, v198
	s_nop 1
	v_permlane32_swap_b32_e32 v68, v69
	v_permlane32_swap_b32_e32 v76, v77
	v_permlane32_swap_b32_e32 v80, v81
	v_permlane32_swap_b32_e32 v84, v85
	v_permlane32_swap_b32_e32 v160, v161
	v_permlane32_swap_b32_e32 v174, v175
	v_permlane32_swap_b32_e32 v178, v179
	v_permlane32_swap_b32_e32 v182, v183
	v_add_f32_e32 v191, v68, v69
	v_add_f32_e32 v192, v76, v77
	v_add_f32_e32 v193, v80, v81
	v_add_f32_e32 v194, v84, v85
	v_add_f32_e32 v195, v160, v161
	v_add_f32_e32 v196, v174, v175
	v_add_f32_e32 v197, v178, v179
	v_add_f32_e32 v198, v182, v183
	v_mov_b32_e32 v200, 0x358637bd
	v_fmamk_f32 v191, v191, 0x3a800000, v200
	v_fmamk_f32 v192, v192, 0x3a800000, v200
	v_fmamk_f32 v193, v193, 0x3a800000, v200
	v_fmamk_f32 v194, v194, 0x3a800000, v200
	v_fmamk_f32 v195, v195, 0x3a800000, v200
	v_fmamk_f32 v196, v196, 0x3a800000, v200
	v_fmamk_f32 v197, v197, 0x3a800000, v200
	v_fmamk_f32 v198, v198, 0x3a800000, v200
	v_rsq_f32_e32 v68, v191
	v_rsq_f32_e32 v76, v192
	v_rsq_f32_e32 v80, v193
	v_rsq_f32_e32 v84, v194
	v_rsq_f32_e32 v160, v195
	v_rsq_f32_e32 v174, v196
	v_rsq_f32_e32 v178, v197
	v_rsq_f32_e32 v182, v198
	s_nop 0
	v_pk_fma_f32 v[140:141], v[140:141], v[68:69], v[144:145] op_sel_hi:[1,0,1]
	v_pk_fma_f32 v[142:143], v[142:143], v[68:69], v[146:147] op_sel_hi:[1,0,1]
	v_pk_fma_f32 v[136:137], v[136:137], v[68:69], v[148:149] op_sel_hi:[1,0,1]
	v_pk_fma_f32 v[138:139], v[138:139], v[68:69], v[150:151] op_sel_hi:[1,0,1]
	v_pk_fma_f32 v[132:133], v[132:133], v[68:69], v[152:153] op_sel_hi:[1,0,1]
	v_pk_fma_f32 v[134:135], v[134:135], v[68:69], v[154:155] op_sel_hi:[1,0,1]
;     __device__ __forceinline__ void operator()(f32x4 (&acc)[2][2][4][2], const Unit& u, int wr, int wc, int fr, int fq) const {
;     ...
;                 for (int m = 0; m < 4; ++m) { const int rl = wr * 64 + fr + ai * HALF + m * 16;
;                     const float rstd = rsv[ai][m];
; #pragma unroll
;                     for (int bj = 0; bj < 2; ++bj) { const f32x4 v0 = acc[ai][bj][m][0] * rstd + bv[bj][0], v1 = acc[ai][bj][m][1] * rstd + bv[bj][1];
;                         acc[ai][bj][m][0] = v0; acc[ai][bj][m][1] = v1;
;                         if (qk) { float sq = ((v0[0] * v0[0] + v0[1] * v0[1]) + (v0[2] * v0[2] + v0[3] * v0[3])) + ((v1[0] * v1[0] + v1[1] * v1[1]) + (v1[2] * v1[2] + v1[3] * v1[3]));
;                             sq += __shfl_xor(sq, 16); sq += __shfl_xor(sq, 32); if (fq == 0) P[(rl * 2 + bj) * 4 + wc] = sq; } } }
;         }
;         if (qk) { asm volatile("s_waitcnt lgkmcnt(0)" ::: "memory"); __builtin_amdgcn_s_barrier(); asm volatile("" ::: "memory"); }
	v_pk_fma_f32 v[128:129], v[128:129], v[68:69], v[156:157] op_sel_hi:[1,0,1]
	v_pk_fma_f32 v[130:131], v[130:131], v[68:69], v[158:159] op_sel_hi:[1,0,1]
	v_pk_fma_f32 v[124:125], v[124:125], v[76:77], v[144:145] op_sel_hi:[1,0,1]
	v_pk_fma_f32 v[126:127], v[126:127], v[76:77], v[146:147] op_sel_hi:[1,0,1]
	v_pk_fma_f32 v[120:121], v[120:121], v[76:77], v[148:149] op_sel_hi:[1,0,1]
	v_pk_fma_f32 v[122:123], v[122:123], v[76:77], v[150:151] op_sel_hi:[1,0,1]
	v_pk_fma_f32 v[116:117], v[116:117], v[76:77], v[152:153] op_sel_hi:[1,0,1]
	v_pk_fma_f32 v[118:119], v[118:119], v[76:77], v[154:155] op_sel_hi:[1,0,1]
	v_pk_fma_f32 v[112:113], v[112:113], v[76:77], v[156:157] op_sel_hi:[1,0,1]
	v_pk_fma_f32 v[114:115], v[114:115], v[76:77], v[158:159] op_sel_hi:[1,0,1]
	v_pk_fma_f32 v[108:109], v[108:109], v[80:81], v[144:145] op_sel_hi:[1,0,1]
	v_pk_fma_f32 v[110:111], v[110:111], v[80:81], v[146:147] op_sel_hi:[1,0,1]
	v_pk_fma_f32 v[104:105], v[104:105], v[80:81], v[148:149] op_sel_hi:[1,0,1]
	v_pk_fma_f32 v[106:107], v[106:107], v[80:81], v[150:151] op_sel_hi:[1,0,1]
	v_pk_fma_f32 v[100:101], v[100:101], v[80:81], v[152:153] op_sel_hi:[1,0,1]
	v_pk_fma_f32 v[102:103], v[102:103], v[80:81], v[154:155] op_sel_hi:[1,0,1]
	v_pk_fma_f32 v[96:97], v[96:97], v[80:81], v[156:157] op_sel_hi:[1,0,1]
	v_pk_fma_f32 v[98:99], v[98:99], v[80:81], v[158:159] op_sel_hi:[1,0,1]
	v_pk_fma_f32 v[92:93], v[92:93], v[84:85], v[144:145] op_sel_hi:[1,0,1]
	v_pk_fma_f32 v[94:95], v[94:95], v[84:85], v[146:147] op_sel_hi:[1,0,1]
	v_pk_fma_f32 v[88:89], v[88:89], v[84:85], v[148:149] op_sel_hi:[1,0,1]
	v_pk_fma_f32 v[90:91], v[90:91], v[84:85], v[150:151] op_sel_hi:[1,0,1]
	v_pk_fma_f32 v[72:73], v[72:73], v[84:85], v[152:153] op_sel_hi:[1,0,1]
	v_pk_fma_f32 v[74:75], v[74:75], v[84:85], v[154:155] op_sel_hi:[1,0,1]
	v_pk_fma_f32 v[64:65], v[64:65], v[84:85], v[156:157] op_sel_hi:[1,0,1]
	v_pk_fma_f32 v[66:67], v[66:67], v[84:85], v[158:159] op_sel_hi:[1,0,1]
	v_pk_fma_f32 v[60:61], v[60:61], v[160:161], v[144:145] op_sel_hi:[1,0,1]
	v_pk_fma_f32 v[62:63], v[62:63], v[160:161], v[146:147] op_sel_hi:[1,0,1]
	v_pk_fma_f32 v[56:57], v[56:57], v[160:161], v[148:149] op_sel_hi:[1,0,1]
	v_pk_fma_f32 v[58:59], v[58:59], v[160:161], v[150:151] op_sel_hi:[1,0,1]
	v_pk_fma_f32 v[52:53], v[52:53], v[160:161], v[152:153] op_sel_hi:[1,0,1]
	v_pk_fma_f32 v[54:55], v[54:55], v[160:161], v[154:155] op_sel_hi:[1,0,1]
	v_pk_fma_f32 v[48:49], v[48:49], v[160:161], v[156:157] op_sel_hi:[1,0,1]
	v_pk_fma_f32 v[50:51], v[50:51], v[160:161], v[158:159] op_sel_hi:[1,0,1]
	v_pk_fma_f32 v[44:45], v[44:45], v[174:175], v[144:145] op_sel_hi:[1,0,1]
	v_pk_fma_f32 v[46:47], v[46:47], v[174:175], v[146:147] op_sel_hi:[1,0,1]
	v_pk_fma_f32 v[40:41], v[40:41], v[174:175], v[148:149] op_sel_hi:[1,0,1]
	v_pk_fma_f32 v[42:43], v[42:43], v[174:175], v[150:151] op_sel_hi:[1,0,1]
	v_pk_fma_f32 v[36:37], v[36:37], v[174:175], v[152:153] op_sel_hi:[1,0,1]
	v_pk_fma_f32 v[38:39], v[38:39], v[174:175], v[154:155] op_sel_hi:[1,0,1]
	v_pk_fma_f32 v[32:33], v[32:33], v[174:175], v[156:157] op_sel_hi:[1,0,1]
	v_pk_fma_f32 v[34:35], v[34:35], v[174:175], v[158:159] op_sel_hi:[1,0,1]
	v_pk_fma_f32 v[28:29], v[28:29], v[178:179], v[144:145] op_sel_hi:[1,0,1]
	v_pk_fma_f32 v[30:31], v[30:31], v[178:179], v[146:147] op_sel_hi:[1,0,1]
	v_pk_fma_f32 v[24:25], v[24:25], v[178:179], v[148:149] op_sel_hi:[1,0,1]
	v_pk_fma_f32 v[26:27], v[26:27], v[178:179], v[150:151] op_sel_hi:[1,0,1]
	v_pk_fma_f32 v[20:21], v[20:21], v[178:179], v[152:153] op_sel_hi:[1,0,1]
	v_pk_fma_f32 v[22:23], v[22:23], v[178:179], v[154:155] op_sel_hi:[1,0,1]
	v_pk_fma_f32 v[16:17], v[16:17], v[178:179], v[156:157] op_sel_hi:[1,0,1]
	v_pk_fma_f32 v[18:19], v[18:19], v[178:179], v[158:159] op_sel_hi:[1,0,1]
	v_pk_fma_f32 v[12:13], v[12:13], v[182:183], v[144:145] op_sel_hi:[1,0,1]
	v_pk_fma_f32 v[14:15], v[14:15], v[182:183], v[146:147] op_sel_hi:[1,0,1]
	v_pk_fma_f32 v[8:9], v[8:9], v[182:183], v[148:149] op_sel_hi:[1,0,1]
	v_pk_fma_f32 v[10:11], v[10:11], v[182:183], v[150:151] op_sel_hi:[1,0,1]
	v_pk_fma_f32 v[4:5], v[4:5], v[182:183], v[152:153] op_sel_hi:[1,0,1]
	v_pk_fma_f32 v[6:7], v[6:7], v[182:183], v[154:155] op_sel_hi:[1,0,1]
	v_pk_fma_f32 v[0:1], v[0:1], v[182:183], v[156:157] op_sel_hi:[1,0,1]
	v_pk_fma_f32 v[2:3], v[2:3], v[182:183], v[158:159] op_sel_hi:[1,0,1]
	s_cmp_gt_i32 s35, 5
	s_cbranch_scc1 .Lqkv_epi_store
;     __device__ __forceinline__ void operator()(f32x4 (&acc)[2][2][4][2], const Unit& u, int wr, int wc, int fr, int fq) const {
;     ...
;                         if (qk) { float sq = ((v0[0] * v0[0] + v0[1] * v0[1]) + (v0[2] * v0[2] + v0[3] * v0[3])) + ((v1[0] * v1[0] + v1[1] * v1[1]) + (v1[2] * v1[2] + v1[3] * v1[3]));
;                             sq += __shfl_xor(sq, 16); sq += __shfl_xor(sq, 32); if (fq == 0) P[(rl * 2 + bj) * 4 + wc] = sq; } } }
;         }
;         if (qk) { asm volatile("s_waitcnt lgkmcnt(0)" ::: "memory"); __builtin_amdgcn_s_barrier(); asm volatile("" ::: "memory"); }
;         float gq[2][4], inv[2][2];
;         { const float* gsrc = u.pn < 4 ? qg : kg;
; #pragma unroll
;           for (int n = 0; n < 2; ++n) {
; #pragma unroll
;             for (int e = 0; e < 4; ++e) { const int p = wc * 32 + 8 * fq + 4 * n + e; gq[n][e] = gsrc[(p >> 6) * 64 + (p & 1) * 32 + ((p & 63) >> 1)]; }
	s_cmp_lt_i32 s35, 4
	s_cselect_b32 s72, s44, s46
	s_cselect_b32 s73, s45, s47
	s_cselect_b32 s74, 0x3e0293ee, 1.0
	s_lshr_b32 s8, s59, 1
	s_lshl_b32 s8, s8, 8
	s_and_b32 s75, s59, 1
	s_lshl_b32 s75, s75, 6
	s_or_b32 s8, s8, s75
	v_lshlrev_b32_e32 v200, 4, v202
	v_or_b32_e32 v200, s8, v200
	global_load_dwordx4 v[144:147], v200, s[72:73]
	global_load_dwordx4 v[148:151], v200, s[72:73] offset:128
	v_pk_mul_f32 v[200:201], v[140:141], v[140:141]
	v_pk_fma_f32 v[200:201], v[142:143], v[142:143], v[200:201]
	v_pk_fma_f32 v[200:201], v[136:137], v[136:137], v[200:201]
	v_pk_fma_f32 v[200:201], v[138:139], v[138:139], v[200:201]
	v_add_f32_e32 v152, v200, v201
	v_pk_mul_f32 v[200:201], v[132:133], v[132:133]
	v_pk_fma_f32 v[200:201], v[134:135], v[134:135], v[200:201]
	v_pk_fma_f32 v[200:201], v[128:129], v[128:129], v[200:201]
	v_pk_fma_f32 v[200:201], v[130:131], v[130:131], v[200:201]
	v_add_f32_e32 v153, v200, v201
	v_pk_mul_f32 v[200:201], v[124:125], v[124:125]
	v_pk_fma_f32 v[200:201], v[126:127], v[126:127], v[200:201]
	v_pk_fma_f32 v[200:201], v[120:121], v[120:121], v[200:201]
	v_pk_fma_f32 v[200:201], v[122:123], v[122:123], v[200:201]
	v_add_f32_e32 v154, v200, v201
	v_pk_mul_f32 v[200:201], v[116:117], v[116:117]
	v_pk_fma_f32 v[200:201], v[118:119], v[118:119], v[200:201]
	v_pk_fma_f32 v[200:201], v[112:113], v[112:113], v[200:201]
	v_pk_fma_f32 v[200:201], v[114:115], v[114:115], v[200:201]
	v_add_f32_e32 v155, v200, v201
	v_pk_mul_f32 v[200:201], v[108:109], v[108:109]
	v_pk_fma_f32 v[200:201], v[110:111], v[110:111], v[200:201]
	v_pk_fma_f32 v[200:201], v[104:105], v[104:105], v[200:201]
	v_pk_fma_f32 v[200:201], v[106:107], v[106:107], v[200:201]
	v_add_f32_e32 v156, v200, v201
	v_pk_mul_f32 v[200:201], v[100:101], v[100:101]
	v_pk_fma_f32 v[200:201], v[102:103], v[102:103], v[200:201]
	v_pk_fma_f32 v[200:201], v[96:97], v[96:97], v[200:201]
	v_pk_fma_f32 v[200:201], v[98:99], v[98:99], v[200:201]
	v_add_f32_e32 v157, v200, v201
	v_pk_mul_f32 v[200:201], v[92:93], v[92:93]
	v_pk_fma_f32 v[200:201], v[94:95], v[94:95], v[200:201]
	v_pk_fma_f32 v[200:201], v[88:89], v[88:89], v[200:201]
	v_pk_fma_f32 v[200:201], v[90:91], v[90:91], v[200:201]
	v_add_f32_e32 v158, v200, v201
	v_pk_mul_f32 v[200:201], v[72:73], v[72:73]
	v_pk_fma_f32 v[200:201], v[74:75], v[74:75], v[200:201]
	v_pk_fma_f32 v[200:201], v[64:65], v[64:65], v[200:201]
	v_pk_fma_f32 v[200:201], v[66:67], v[66:67], v[200:201]
	v_add_f32_e32 v159, v200, v201
	v_pk_mul_f32 v[200:201], v[60:61], v[60:61]
	v_pk_fma_f32 v[200:201], v[62:63], v[62:63], v[200:201]
	v_pk_fma_f32 v[200:201], v[56:57], v[56:57], v[200:201]
	v_pk_fma_f32 v[200:201], v[58:59], v[58:59], v[200:201]
	v_add_f32_e32 v191, v200, v201
	v_pk_mul_f32 v[200:201], v[52:53], v[52:53]
	v_pk_fma_f32 v[200:201], v[54:55], v[54:55], v[200:201]
	v_pk_fma_f32 v[200:201], v[48:49], v[48:49], v[200:201]
	v_pk_fma_f32 v[200:201], v[50:51], v[50:51], v[200:201]
	v_add_f32_e32 v192, v200, v201
	v_pk_mul_f32 v[200:201], v[44:45], v[44:45]
	v_pk_fma_f32 v[200:201], v[46:47], v[46:47], v[200:201]
	v_pk_fma_f32 v[200:201], v[40:41], v[40:41], v[200:201]
	v_pk_fma_f32 v[200:201], v[42:43], v[42:43], v[200:201]
	v_add_f32_e32 v193, v200, v201
	v_pk_mul_f32 v[200:201], v[36:37], v[36:37]
	v_pk_fma_f32 v[200:201], v[38:39], v[38:39], v[200:201]
	v_pk_fma_f32 v[200:201], v[32:33], v[32:33], v[200:201]
	v_pk_fma_f32 v[200:201], v[34:35], v[34:35], v[200:201]
	v_add_f32_e32 v194, v200, v201
	v_pk_mul_f32 v[200:201], v[28:29], v[28:29]
	v_pk_fma_f32 v[200:201], v[30:31], v[30:31], v[200:201]
	v_pk_fma_f32 v[200:201], v[24:25], v[24:25], v[200:201]
	v_pk_fma_f32 v[200:201], v[26:27], v[26:27], v[200:201]
	v_add_f32_e32 v195, v200, v201
	v_pk_mul_f32 v[200:201], v[20:21], v[20:21]
	v_pk_fma_f32 v[200:201], v[22:23], v[22:23], v[200:201]
	v_pk_fma_f32 v[200:201], v[16:17], v[16:17], v[200:201]
	v_pk_fma_f32 v[200:201], v[18:19], v[18:19], v[200:201]
	v_add_f32_e32 v196, v200, v201
	v_pk_mul_f32 v[200:201], v[12:13], v[12:13]
	v_pk_fma_f32 v[200:201], v[14:15], v[14:15], v[200:201]
	v_pk_fma_f32 v[200:201], v[8:9], v[8:9], v[200:201]
	v_pk_fma_f32 v[200:201], v[10:11], v[10:11], v[200:201]
	v_add_f32_e32 v197, v200, v201
	v_pk_mul_f32 v[200:201], v[4:5], v[4:5]
	v_pk_fma_f32 v[200:201], v[6:7], v[6:7], v[200:201]
	v_pk_fma_f32 v[200:201], v[0:1], v[0:1], v[200:201]
	v_pk_fma_f32 v[200:201], v[2:3], v[2:3], v[200:201]
	v_add_f32_e32 v198, v200, v201
	v_mov_b32_e32 v68, v152
	v_mov_b32_e32 v69, v152
	v_mov_b32_e32 v76, v153
	v_mov_b32_e32 v77, v153
	v_mov_b32_e32 v80, v154
	v_mov_b32_e32 v81, v154
	v_mov_b32_e32 v84, v155
	v_mov_b32_e32 v85, v155
	v_mov_b32_e32 v160, v156
	v_mov_b32_e32 v161, v156
	v_mov_b32_e32 v174, v157
	v_mov_b32_e32 v175, v157
	v_mov_b32_e32 v178, v158
	v_mov_b32_e32 v179, v158
	v_mov_b32_e32 v182, v159
	v_mov_b32_e32 v183, v159
	s_nop 1
	v_permlane16_swap_b32_e32 v68, v69
	v_permlane16_swap_b32_e32 v76, v77
	v_permlane16_swap_b32_e32 v80, v81
	v_permlane16_swap_b32_e32 v84, v85
	v_permlane16_swap_b32_e32 v160, v161
	v_permlane16_swap_b32_e32 v174, v175
	v_permlane16_swap_b32_e32 v178, v179
	v_permlane16_swap_b32_e32 v182, v183
	v_add_f32_e32 v152, v68, v69
	v_add_f32_e32 v153, v76, v77
	v_add_f32_e32 v154, v80, v81
	v_add_f32_e32 v155, v84, v85
	v_add_f32_e32 v156, v160, v161
	v_add_f32_e32 v157, v174, v175
	v_add_f32_e32 v158, v178, v179
	v_add_f32_e32 v159, v182, v183
	v_mov_b32_e32 v68, v152
	v_mov_b32_e32 v69, v152
	v_mov_b32_e32 v76, v153
	v_mov_b32_e32 v77, v153
	v_mov_b32_e32 v80, v154
	v_mov_b32_e32 v81, v154
	v_mov_b32_e32 v84, v155
	v_mov_b32_e32 v85, v155
	v_mov_b32_e32 v160, v156
	v_mov_b32_e32 v161, v156
; #define PG8_LAS __attribute__((address_space(3)))
;     __device__ __forceinline__ void operator()(f32x4 (&acc)[2][2][4][2], const Unit& u, int wr, int wc, int fr, int fq) const {
;     ...
;                         if (qk) { float sq = ((v0[0] * v0[0] + v0[1] * v0[1]) + (v0[2] * v0[2] + v0[3] * v0[3])) + ((v1[0] * v1[0] + v1[1] * v1[1]) + (v1[2] * v1[2] + v1[3] * v1[3]));
;                             sq += __shfl_xor(sq, 16); sq += __shfl_xor(sq, 32); if (fq == 0) P[(rl * 2 + bj) * 4 + wc] = sq; } } }
;         }
;         if (qk) { asm volatile("s_waitcnt lgkmcnt(0)" ::: "memory"); __builtin_amdgcn_s_barrier(); asm volatile("" ::: "memory"); }
;     ...
;                     if (qk) { const f32x4 pt = *(const PG8_LAS f32x4*)(P + (rl * 2 + bj) * 4);
;                         const float hr = rsqrtf(((pt[0] + pt[1]) + (pt[2] + pt[3])) * (1.f / 128.f) + EPS);
	v_mov_b32_e32 v174, v157
	v_mov_b32_e32 v175, v157
	v_mov_b32_e32 v178, v158
	v_mov_b32_e32 v179, v158
	v_mov_b32_e32 v182, v159
	v_mov_b32_e32 v183, v159
	s_nop 1
	v_permlane32_swap_b32_e32 v68, v69
	v_permlane32_swap_b32_e32 v76, v77
	v_permlane32_swap_b32_e32 v80, v81
	v_permlane32_swap_b32_e32 v84, v85
	v_permlane32_swap_b32_e32 v160, v161
	v_permlane32_swap_b32_e32 v174, v175
	v_permlane32_swap_b32_e32 v178, v179
	v_permlane32_swap_b32_e32 v182, v183
	v_add_f32_e32 v152, v68, v69
	v_add_f32_e32 v153, v76, v77
	v_add_f32_e32 v154, v80, v81
	v_add_f32_e32 v155, v84, v85
	v_add_f32_e32 v156, v160, v161
	v_add_f32_e32 v157, v174, v175
	v_add_f32_e32 v158, v178, v179
	v_add_f32_e32 v159, v182, v183
	v_mov_b32_e32 v68, v191
	v_mov_b32_e32 v69, v191
	v_mov_b32_e32 v76, v192
	v_mov_b32_e32 v77, v192
	v_mov_b32_e32 v80, v193
	v_mov_b32_e32 v81, v193
	v_mov_b32_e32 v84, v194
	v_mov_b32_e32 v85, v194
	v_mov_b32_e32 v160, v195
	v_mov_b32_e32 v161, v195
	v_mov_b32_e32 v174, v196
	v_mov_b32_e32 v175, v196
	v_mov_b32_e32 v178, v197
	v_mov_b32_e32 v179, v197
	v_mov_b32_e32 v182, v198
	v_mov_b32_e32 v183, v198
	s_nop 1
	v_permlane16_swap_b32_e32 v68, v69
	v_permlane16_swap_b32_e32 v76, v77
	v_permlane16_swap_b32_e32 v80, v81
	v_permlane16_swap_b32_e32 v84, v85
	v_permlane16_swap_b32_e32 v160, v161
	v_permlane16_swap_b32_e32 v174, v175
	v_permlane16_swap_b32_e32 v178, v179
	v_permlane16_swap_b32_e32 v182, v183
	v_add_f32_e32 v191, v68, v69
	v_add_f32_e32 v192, v76, v77
	v_add_f32_e32 v193, v80, v81
	v_add_f32_e32 v194, v84, v85
	v_add_f32_e32 v195, v160, v161
	v_add_f32_e32 v196, v174, v175
	v_add_f32_e32 v197, v178, v179
	v_add_f32_e32 v198, v182, v183
	v_mov_b32_e32 v68, v191
	v_mov_b32_e32 v69, v191
	v_mov_b32_e32 v76, v192
	v_mov_b32_e32 v77, v192
	v_mov_b32_e32 v80, v193
	v_mov_b32_e32 v81, v193
	v_mov_b32_e32 v84, v194
	v_mov_b32_e32 v85, v194
	v_mov_b32_e32 v160, v195
	v_mov_b32_e32 v161, v195
	v_mov_b32_e32 v174, v196
	v_mov_b32_e32 v175, v196
	v_mov_b32_e32 v178, v197
	v_mov_b32_e32 v179, v197
	v_mov_b32_e32 v182, v198
	v_mov_b32_e32 v183, v198
	s_nop 1
	v_permlane32_swap_b32_e32 v68, v69
	v_permlane32_swap_b32_e32 v76, v77
	v_permlane32_swap_b32_e32 v80, v81
	v_permlane32_swap_b32_e32 v84, v85
	v_permlane32_swap_b32_e32 v160, v161
	v_permlane32_swap_b32_e32 v174, v175
	v_permlane32_swap_b32_e32 v178, v179
	v_permlane32_swap_b32_e32 v182, v183
	v_add_f32_e32 v191, v68, v69
	v_add_f32_e32 v192, v76, v77
	v_add_f32_e32 v193, v80, v81
	v_add_f32_e32 v194, v84, v85
	v_add_f32_e32 v195, v160, v161
	v_add_f32_e32 v196, v174, v175
	v_add_f32_e32 v197, v178, v179
	v_add_f32_e32 v198, v182, v183
	s_lshl_b32 s8, s59, 2
	s_add_i32 s8, s8, 0x20000
	v_lshl_add_u32 v199, v203, 5, s8
	s_mov_b64 s[72:73], exec
	s_mov_b64 exec, 0xffff
	ds_write_b32 v199, v152 offset:0
	ds_write_b32 v199, v153 offset:16
	ds_write_b32 v199, v154 offset:512
	ds_write_b32 v199, v155 offset:528
	ds_write_b32 v199, v156 offset:1024
	ds_write_b32 v199, v157 offset:1040
	ds_write_b32 v199, v158 offset:1536
	ds_write_b32 v199, v159 offset:1552
	ds_write_b32 v199, v191 offset:4096
	ds_write_b32 v199, v192 offset:4112
	ds_write_b32 v199, v193 offset:4608
	ds_write_b32 v199, v194 offset:4624
	ds_write_b32 v199, v195 offset:5120
	ds_write_b32 v199, v196 offset:5136
	ds_write_b32 v199, v197 offset:5632
	ds_write_b32 v199, v198 offset:5648
	s_mov_b64 exec, s[72:73]
	s_waitcnt lgkmcnt(0)
	s_barrier
	v_lshlrev_b32_e32 v199, 5, v203
	v_add_u32_e32 v199, 0x20000, v199
	v_mov_b32_e32 v200, 0x358637bd
	ds_read_b128 v[68:71], v199 offset:0
	ds_read_b128 v[76:79], v199 offset:16
	ds_read_b128 v[80:83], v199 offset:512
	ds_read_b128 v[84:87], v199 offset:528
	ds_read_b128 v[160:163], v199 offset:1024
	ds_read_b128 v[174:177], v199 offset:1040
	ds_read_b128 v[178:181], v199 offset:1536
	ds_read_b128 v[182:185], v199 offset:1552
	s_waitcnt lgkmcnt(0)
	v_add_f32_e32 v68, v68, v69
	v_add_f32_e32 v70, v70, v71
	v_add_f32_e32 v76, v76, v77
	v_add_f32_e32 v78, v78, v79
	v_add_f32_e32 v80, v80, v81
	v_add_f32_e32 v82, v82, v83
	v_add_f32_e32 v84, v84, v85
	v_add_f32_e32 v86, v86, v87
	v_add_f32_e32 v160, v160, v161
	v_add_f32_e32 v162, v162, v163
	v_add_f32_e32 v174, v174, v175
	v_add_f32_e32 v176, v176, v177
	v_add_f32_e32 v178, v178, v179
	v_add_f32_e32 v180, v180, v181
	v_add_f32_e32 v182, v182, v183
	v_add_f32_e32 v184, v184, v185
	v_add_f32_e32 v152, v68, v70
	v_add_f32_e32 v153, v76, v78
	v_add_f32_e32 v154, v80, v82
	v_add_f32_e32 v155, v84, v86
	v_add_f32_e32 v156, v160, v162
	v_add_f32_e32 v157, v174, v176
	v_add_f32_e32 v158, v178, v180
	v_add_f32_e32 v159, v182, v184
	v_fmamk_f32 v152, v152, 0x3c000000, v200
	v_fmamk_f32 v153, v153, 0x3c000000, v200
	v_fmamk_f32 v154, v154, 0x3c000000, v200
	v_fmamk_f32 v155, v155, 0x3c000000, v200
	v_fmamk_f32 v156, v156, 0x3c000000, v200
	v_fmamk_f32 v157, v157, 0x3c000000, v200
	v_fmamk_f32 v158, v158, 0x3c000000, v200
	v_fmamk_f32 v159, v159, 0x3c000000, v200
	v_rsq_f32_e32 v152, v152
	v_rsq_f32_e32 v153, v153
	v_rsq_f32_e32 v154, v154
	v_rsq_f32_e32 v155, v155
	v_rsq_f32_e32 v156, v156
	v_rsq_f32_e32 v157, v157
	v_rsq_f32_e32 v158, v158
	v_rsq_f32_e32 v159, v159
	ds_read_b128 v[68:71], v199 offset:4096
	ds_read_b128 v[76:79], v199 offset:4112
	ds_read_b128 v[80:83], v199 offset:4608
	ds_read_b128 v[84:87], v199 offset:4624
	ds_read_b128 v[160:163], v199 offset:5120
	ds_read_b128 v[174:177], v199 offset:5136
	ds_read_b128 v[178:181], v199 offset:5632
	ds_read_b128 v[182:185], v199 offset:5648
	s_waitcnt lgkmcnt(0)
; #define PG8_LAS __attribute__((address_space(3)))
;     __device__ __forceinline__ void operator()(f32x4 (&acc)[2][2][4][2], const Unit& u, int wr, int wc, int fr, int fq) const {
;     ...
;         float gq[2][4], inv[2][2];
;         { const float* gsrc = u.pn < 4 ? qg : kg;
; #pragma unroll
;           for (int n = 0; n < 2; ++n) {
; #pragma unroll
;             for (int e = 0; e < 4; ++e) { const int p = wc * 32 + 8 * fq + 4 * n + e; gq[n][e] = gsrc[(p >> 6) * 64 + (p & 1) * 32 + ((p & 63) >> 1)]; }
; #pragma unroll
;             for (int pr = 0; pr < 2; ++pr) inv[n][pr] = __builtin_amdgcn_exp2f(-(float)(16 * (wc & 1) + 4 * fq + 2 * n + pr) * 0.4152410118609203f); } }
;         const int headbase = (u.pn & 1) * 2;
; #pragma unroll
;         for (int ai = 0; ai < 2; ++ai)
; #pragma unroll
;             for (int m = 0; m < 4; ++m) { const int rl = wr * 64 + fr + ai * HALF + m * 16, row = rowt + rl;
;                 int kvrow; float cs[2][2], sn[2][2];
;                 if (is_lat) { const int t = row & (SEQ - 1); kvrow = b * SKV + CTXL + t; const float pos = (float)((wc >> 1) ? (t & 63) : (t >> 6));
; #pragma unroll
;                     for (int n = 0; n < 2; ++n)
; #pragma unroll
;                         for (int pr = 0; pr < 2; ++pr) { const float a = pos * inv[n][pr]; cs[n][pr] = __cosf(a); sn[n][pr] = __sinf(a); } }
;                 else { kvrow = ((row - MLAT) >> 8) * SKV + ((row - MLAT) & (CTXL - 1));
; #pragma unroll
;                     for (int n = 0; n < 2; ++n)
; #pragma unroll
;                         for (int pr = 0; pr < 2; ++pr) { cs[n][pr] = 1.f; sn[n][pr] = 0.f; } }
; #pragma unroll
;                 for (int bj = 0; bj < 2; ++bj) { f32x4 v0 = acc[ai][bj][m][0], v1 = acc[ai][bj][m][1]; bf16_t* dst;
;                     if (qk) { const f32x4 pt = *(const PG8_LAS f32x4*)(P + (rl * 2 + bj) * 4);
;                         const float hr = rsqrtf(((pt[0] + pt[1]) + (pt[2] + pt[3])) * (1.f / 128.f) + EPS);
; #pragma unroll
;                         for (int e = 0; e < 4; ++e) { v0[e] = v0[e] * hr * gq[0][e]; v1[e] = v1[e] * hr * gq[1][e]; }
;                         const f32x4 r0 = {v0[0] * cs[0][0] - v0[1] * sn[0][0], v0[0] * sn[0][0] + v0[1] * cs[0][0], v0[2] * cs[0][1] - v0[3] * sn[0][1], v0[2] * sn[0][1] + v0[3] * cs[0][1]};
	v_add_f32_e32 v68, v68, v69
	v_add_f32_e32 v70, v70, v71
	v_add_f32_e32 v76, v76, v77
	v_add_f32_e32 v78, v78, v79
	v_add_f32_e32 v80, v80, v81
	v_add_f32_e32 v82, v82, v83
	v_add_f32_e32 v84, v84, v85
	v_add_f32_e32 v86, v86, v87
	v_add_f32_e32 v160, v160, v161
	v_add_f32_e32 v162, v162, v163
	v_add_f32_e32 v174, v174, v175
	v_add_f32_e32 v176, v176, v177
	v_add_f32_e32 v178, v178, v179
	v_add_f32_e32 v180, v180, v181
	v_add_f32_e32 v182, v182, v183
	v_add_f32_e32 v184, v184, v185
	v_add_f32_e32 v191, v68, v70
	v_add_f32_e32 v192, v76, v78
	v_add_f32_e32 v193, v80, v82
	v_add_f32_e32 v194, v84, v86
	v_add_f32_e32 v195, v160, v162
	v_add_f32_e32 v196, v174, v176
	v_add_f32_e32 v197, v178, v180
	v_add_f32_e32 v198, v182, v184
	v_fmamk_f32 v191, v191, 0x3c000000, v200
	v_fmamk_f32 v192, v192, 0x3c000000, v200
	v_fmamk_f32 v193, v193, 0x3c000000, v200
	v_fmamk_f32 v194, v194, 0x3c000000, v200
	v_fmamk_f32 v195, v195, 0x3c000000, v200
	v_fmamk_f32 v196, v196, 0x3c000000, v200
	v_fmamk_f32 v197, v197, 0x3c000000, v200
	v_fmamk_f32 v198, v198, 0x3c000000, v200
	v_rsq_f32_e32 v191, v191
	v_rsq_f32_e32 v192, v192
	v_rsq_f32_e32 v193, v193
	v_rsq_f32_e32 v194, v194
	v_rsq_f32_e32 v195, v195
	v_rsq_f32_e32 v196, v196
	v_rsq_f32_e32 v197, v197
	v_rsq_f32_e32 v198, v198
	s_waitcnt vmcnt(0)
	v_mul_f32_e32 v144, s74, v144
	v_mul_f32_e32 v145, s74, v145
	v_mul_f32_e32 v146, s74, v146
	v_mul_f32_e32 v147, s74, v147
	v_mul_f32_e32 v148, s74, v148
	v_mul_f32_e32 v149, s74, v149
	v_mul_f32_e32 v150, s74, v150
	v_mul_f32_e32 v151, s74, v151
	s_and_b32 s8, s59, 1
	s_lshl_b32 s8, s8, 4
	v_lshl_add_u32 v200, v202, 2, s8
	v_add_u32_e32 v84, 0, v200
	v_add_u32_e32 v85, 1, v200
	v_add_u32_e32 v86, 2, v200
	v_add_u32_e32 v87, 3, v200
	v_cvt_f32_u32_e32 v84, v84
	v_cvt_f32_u32_e32 v85, v85
	v_cvt_f32_u32_e32 v86, v86
	v_cvt_f32_u32_e32 v87, v87
	v_mul_f32_e32 v84, 0xbed49a78, v84
	v_mul_f32_e32 v85, 0xbed49a78, v85
	v_mul_f32_e32 v86, 0xbed49a78, v86
	v_mul_f32_e32 v87, 0xbed49a78, v87
	v_exp_f32_e32 v84, v84
	v_exp_f32_e32 v85, v85
	v_exp_f32_e32 v86, v86
	v_exp_f32_e32 v87, v87
	s_nop 0
	v_lshl_add_u32 v70, s42, 8, v203
	v_mov_b32_e32 v71, 0
	s_cmp_lt_i32 s35, 4
	s_cbranch_scc1 .Lqkv_epi_dstq
.Lqkv_epi_store:
	s_cmp_gt_i32 s35, 5
	s_cselect_b32 s8, 6, 4
	s_sub_i32 s8, s35, s8
	s_lshl_b32 s8, s8, 9
	s_mov_b32 s72, 0xda00000
	s_mov_b32 s73, 0xeb00000
	s_cmp_gt_i32 s35, 5
	s_cselect_b32 s72, s73, s72
	s_add_u32 s72, s20, s72
	s_addc_u32 s73, s21, 0
	s_add_u32 s72, s72, s8
	s_addc_u32 s73, s73, 0
	s_lshr_b32 s8, s42, 5
	s_mul_i32 s8, s8, 0x2100
	s_and_b32 s75, s42, 31
	s_lshl_b32 s75, s75, 8
	s_add_i32 s8, s8, s75
	s_addk_i32 s8, 0x100
	s_sub_i32 s75, s42, 64
	s_mul_i32 s75, s75, 0x2100
	s_cmp_gt_i32 s42, 63
	s_cselect_b32 s8, s75, s8
	v_add_u32_e32 v68, s8, v203
	v_mov_b32_e32 v69, 0
	v_lshlrev_b64 v[68:69], 10, v[68:69]
	s_mov_b64 s[76:77], 0x4000
	s_mov_b64 s[78:79], 0x14000
	s_branch .Lqkv_epi_dstdone
.Lqkv_epi_dstq:
	s_lshl_b32 s8, s35, 9
	s_add_u32 s72, s20, 0xba00000
	s_addc_u32 s73, s21, 0
	s_add_u32 s72, s72, s8
	s_addc_u32 s73, s73, 0
	v_lshlrev_b64 v[68:69], 11, v[70:71]
	s_mov_b64 s[76:77], 0x8000
	s_mov_b64 s[78:79], 0x28000
.Lqkv_epi_dstdone:
	v_lshl_add_u64 v[68:69], s[72:73], 0, v[68:69]
	s_lshl_b32 s8, s59, 6
	v_lshl_add_u32 v200, v202, 4, s8
	v_mov_b32_e32 v201, 0
	v_lshl_add_u64 v[68:69], v[68:69], 0, v[200:201]
	s_cmp_gt_i32 s35, 5
	s_cbranch_scc1 .Lqkv_epi_vrows
	s_cmp_gt_i32 s42, 63
	s_cselect_b32 s74, 1, 0
	v_add_u32_e32 v200, 0, v70
	v_and_b32_e32 v200, 0x1fff, v200
	v_and_b32_e32 v201, 63, v200
	v_lshrrev_b32_e32 v200, 6, v200
	s_cmp_gt_u32 s59, 1
	s_cselect_b64 vcc, -1, 0
	v_cndmask_b32_e32 v200, v200, v201, vcc
	v_cvt_f32_u32_e32 v200, v200
	v_mul_f32_e32 v76, v200, v84
	v_mul_f32_e32 v77, v200, v85
	v_mul_f32_e32 v78, v200, v86
	v_mul_f32_e32 v79, v200, v87
	v_mul_f32_e32 v76, 0.15915494, v76
	v_mul_f32_e32 v77, 0.15915494, v77
	v_mul_f32_e32 v78, 0.15915494, v78
	v_mul_f32_e32 v79, 0.15915494, v79
	v_sin_f32_e32 v80, v76
	v_sin_f32_e32 v81, v77
	v_sin_f32_e32 v82, v78
	v_sin_f32_e32 v83, v79
	v_cos_f32_e32 v76, v76
	v_cos_f32_e32 v77, v77
	v_cos_f32_e32 v78, v78
	v_cos_f32_e32 v79, v79
	s_cmp_lg_u32 s74, 0
	s_cselect_b64 vcc, -1, 0
	v_cndmask_b32_e64 v76, v76, 1.0, vcc
	v_cndmask_b32_e64 v80, v80, 0, vcc
	v_cndmask_b32_e64 v77, v77, 1.0, vcc
	v_cndmask_b32_e64 v81, v81, 0, vcc
	v_cndmask_b32_e64 v78, v78, 1.0, vcc
	v_cndmask_b32_e64 v82, v82, 0, vcc
	v_cndmask_b32_e64 v79, v79, 1.0, vcc
	v_cndmask_b32_e64 v83, v83, 0, vcc
	v_mul_f32_e32 v140, v140, v152
	v_mul_f32_e32 v141, v141, v152
	v_mul_f32_e32 v142, v142, v152
	v_mul_f32_e32 v143, v143, v152
	v_mul_f32_e32 v136, v136, v152
	v_mul_f32_e32 v137, v137, v152
	v_mul_f32_e32 v138, v138, v152
	v_mul_f32_e32 v139, v139, v152
	v_mul_f32_e32 v140, v140, v144
	v_mul_f32_e32 v141, v141, v148
	v_mul_f32_e32 v142, v142, v145
	v_mul_f32_e32 v143, v143, v149
	v_mul_f32_e32 v136, v136, v146
	v_mul_f32_e32 v137, v137, v150
	v_mul_f32_e32 v138, v138, v147
	v_mul_f32_e32 v139, v139, v151
	v_mul_f32_e32 v174, v141, v80
	v_mul_f32_e32 v175, v141, v76
	v_mul_f32_e32 v176, v143, v81
	v_mul_f32_e32 v177, v143, v77
	v_mul_f32_e32 v178, v137, v82
	v_mul_f32_e32 v179, v137, v78
	v_mul_f32_e32 v180, v139, v83
	v_mul_f32_e32 v181, v139, v79
	v_fma_f32 v174, v140, v76, -v174
	v_fma_f32 v175, v140, v80, v175
	v_fma_f32 v176, v142, v77, -v176
	v_fma_f32 v177, v142, v81, v177
	v_fma_f32 v178, v136, v78, -v178
	v_fma_f32 v179, v136, v82, v179
	v_fma_f32 v180, v138, v79, -v180
	v_fma_f32 v181, v138, v83, v181
	v_cvt_pk_bf16_f32 v160, v174, v175
	v_cvt_pk_bf16_f32 v161, v176, v177
	v_cvt_pk_bf16_f32 v162, v178, v179
;     __device__ __forceinline__ void operator()(f32x4 (&acc)[2][2][4][2], const Unit& u, int wr, int wc, int fr, int fq) const {
;     ...
; #pragma unroll
;         for (int ai = 0; ai < 2; ++ai)
; #pragma unroll
;             for (int m = 0; m < 4; ++m) { const int rl = wr * 64 + fr + ai * HALF + m * 16, row = rowt + rl;
;                 int kvrow; float cs[2][2], sn[2][2];
;                 if (is_lat) { const int t = row & (SEQ - 1); kvrow = b * SKV + CTXL + t; const float pos = (float)((wc >> 1) ? (t & 63) : (t >> 6));
; #pragma unroll
;                     for (int n = 0; n < 2; ++n)
; #pragma unroll
;                         for (int pr = 0; pr < 2; ++pr) { const float a = pos * inv[n][pr]; cs[n][pr] = __cosf(a); sn[n][pr] = __sinf(a); } }
;                 else { kvrow = ((row - MLAT) >> 8) * SKV + ((row - MLAT) & (CTXL - 1));
; #pragma unroll
;                     for (int n = 0; n < 2; ++n)
; #pragma unroll
;                         for (int pr = 0; pr < 2; ++pr) { cs[n][pr] = 1.f; sn[n][pr] = 0.f; } }
; #pragma unroll
;                 for (int bj = 0; bj < 2; ++bj) { f32x4 v0 = acc[ai][bj][m][0], v1 = acc[ai][bj][m][1]; bf16_t* dst;
;                     if (qk) { const f32x4 pt = *(const PG8_LAS f32x4*)(P + (rl * 2 + bj) * 4);
;                         const float hr = rsqrtf(((pt[0] + pt[1]) + (pt[2] + pt[3])) * (1.f / 128.f) + EPS);
; #pragma unroll
;                         for (int e = 0; e < 4; ++e) { v0[e] = v0[e] * hr * gq[0][e]; v1[e] = v1[e] * hr * gq[1][e]; }
;                         const f32x4 r0 = {v0[0] * cs[0][0] - v0[1] * sn[0][0], v0[0] * sn[0][0] + v0[1] * cs[0][0], v0[2] * cs[0][1] - v0[3] * sn[0][1], v0[2] * sn[0][1] + v0[3] * cs[0][1]};
;                         const f32x4 r1 = {v1[0] * cs[1][0] - v1[1] * sn[1][0], v1[0] * sn[1][0] + v1[1] * cs[1][0], v1[2] * cs[1][1] - v1[3] * sn[1][1], v1[2] * sn[1][1] + v1[3] * cs[1][1]};
;                         v0 = r0; v1 = r1;
;                         dst = u.pn < 4 ? Q + (size_t)row * DM + (u.pn * 2 + bj) * 128 : K + (size_t)kvrow * 512 + ((u.pn - 4) * 2 + bj) * 128;
;                     } else dst = V + (size_t)kvrow * 512 + ((u.pn - 6) * 2 + bj) * 128;
;                     u32x4 w; w.x = cvt_pk_bf16(v0[0], v0[1]); w.y = cvt_pk_bf16(v0[2], v0[3]); w.z = cvt_pk_bf16(v1[0], v1[1]); w.w = cvt_pk_bf16(v1[2], v1[3]);
;                     *(u32x4*)(dst + wc * 32 + 8 * fq) = w; } }
	v_cvt_pk_bf16_f32 v163, v180, v181
	global_store_dwordx4 v[68:69], v[160:163], off sc1
	v_mul_f32_e32 v132, v132, v153
	v_mul_f32_e32 v133, v133, v153
	v_mul_f32_e32 v134, v134, v153
	v_mul_f32_e32 v135, v135, v153
	v_mul_f32_e32 v128, v128, v153
	v_mul_f32_e32 v129, v129, v153
	v_mul_f32_e32 v130, v130, v153
	v_mul_f32_e32 v131, v131, v153
	v_mul_f32_e32 v132, v132, v144
	v_mul_f32_e32 v133, v133, v148
	v_mul_f32_e32 v134, v134, v145
	v_mul_f32_e32 v135, v135, v149
	v_mul_f32_e32 v128, v128, v146
	v_mul_f32_e32 v129, v129, v150
	v_mul_f32_e32 v130, v130, v147
	v_mul_f32_e32 v131, v131, v151
	v_mul_f32_e32 v174, v133, v80
	v_mul_f32_e32 v175, v133, v76
	v_mul_f32_e32 v176, v135, v81
	v_mul_f32_e32 v177, v135, v77
	v_mul_f32_e32 v178, v129, v82
	v_mul_f32_e32 v179, v129, v78
	v_mul_f32_e32 v180, v131, v83
	v_mul_f32_e32 v181, v131, v79
	v_fma_f32 v174, v132, v76, -v174
	v_fma_f32 v175, v132, v80, v175
	v_fma_f32 v176, v134, v77, -v176
	v_fma_f32 v177, v134, v81, v177
	v_fma_f32 v178, v128, v78, -v178
	v_fma_f32 v179, v128, v82, v179
	v_fma_f32 v180, v130, v79, -v180
	v_fma_f32 v181, v130, v83, v181
	v_cvt_pk_bf16_f32 v182, v174, v175
	v_cvt_pk_bf16_f32 v183, v176, v177
	v_cvt_pk_bf16_f32 v184, v178, v179
	v_cvt_pk_bf16_f32 v185, v180, v181
	global_store_dwordx4 v[68:69], v[182:185], off offset:256 sc1
	v_add_u32_e32 v200, 16, v70
	v_and_b32_e32 v200, 0x1fff, v200
	v_and_b32_e32 v201, 63, v200
	v_lshrrev_b32_e32 v200, 6, v200
	s_cmp_gt_u32 s59, 1
	s_cselect_b64 vcc, -1, 0
	v_cndmask_b32_e32 v200, v200, v201, vcc
	v_cvt_f32_u32_e32 v200, v200
	v_mul_f32_e32 v76, v200, v84
	v_mul_f32_e32 v77, v200, v85
	v_mul_f32_e32 v78, v200, v86
	v_mul_f32_e32 v79, v200, v87
	v_mul_f32_e32 v76, 0.15915494, v76
	v_mul_f32_e32 v77, 0.15915494, v77
	v_mul_f32_e32 v78, 0.15915494, v78
	v_mul_f32_e32 v79, 0.15915494, v79
	v_sin_f32_e32 v80, v76
	v_sin_f32_e32 v81, v77
	v_sin_f32_e32 v82, v78
	v_sin_f32_e32 v83, v79
	v_cos_f32_e32 v76, v76
	v_cos_f32_e32 v77, v77
	v_cos_f32_e32 v78, v78
	v_cos_f32_e32 v79, v79
	s_cmp_lg_u32 s74, 0
	s_cselect_b64 vcc, -1, 0
	v_cndmask_b32_e64 v76, v76, 1.0, vcc
	v_cndmask_b32_e64 v80, v80, 0, vcc
	v_cndmask_b32_e64 v77, v77, 1.0, vcc
	v_cndmask_b32_e64 v81, v81, 0, vcc
	v_cndmask_b32_e64 v78, v78, 1.0, vcc
	v_cndmask_b32_e64 v82, v82, 0, vcc
	v_cndmask_b32_e64 v79, v79, 1.0, vcc
	v_cndmask_b32_e64 v83, v83, 0, vcc
	v_lshl_add_u64 v[68:69], v[68:69], 0, s[76:77]
	v_mul_f32_e32 v124, v124, v154
	v_mul_f32_e32 v125, v125, v154
	v_mul_f32_e32 v126, v126, v154
	v_mul_f32_e32 v127, v127, v154
	v_mul_f32_e32 v120, v120, v154
	v_mul_f32_e32 v121, v121, v154
	v_mul_f32_e32 v122, v122, v154
	v_mul_f32_e32 v123, v123, v154
	v_mul_f32_e32 v124, v124, v144
	v_mul_f32_e32 v125, v125, v148
	v_mul_f32_e32 v126, v126, v145
	v_mul_f32_e32 v127, v127, v149
	v_mul_f32_e32 v120, v120, v146
	v_mul_f32_e32 v121, v121, v150
	v_mul_f32_e32 v122, v122, v147
	v_mul_f32_e32 v123, v123, v151
	v_mul_f32_e32 v174, v125, v80
	v_mul_f32_e32 v175, v125, v76
	v_mul_f32_e32 v176, v127, v81
	v_mul_f32_e32 v177, v127, v77
	v_mul_f32_e32 v178, v121, v82
	v_mul_f32_e32 v179, v121, v78
	v_mul_f32_e32 v180, v123, v83
	v_mul_f32_e32 v181, v123, v79
	v_fma_f32 v174, v124, v76, -v174
	v_fma_f32 v175, v124, v80, v175
	v_fma_f32 v176, v126, v77, -v176
	v_fma_f32 v177, v126, v81, v177
	v_fma_f32 v178, v120, v78, -v178
	v_fma_f32 v179, v120, v82, v179
	v_fma_f32 v180, v122, v79, -v180
	v_fma_f32 v181, v122, v83, v181
	v_cvt_pk_bf16_f32 v160, v174, v175
	v_cvt_pk_bf16_f32 v161, v176, v177
	v_cvt_pk_bf16_f32 v162, v178, v179
	v_cvt_pk_bf16_f32 v163, v180, v181
	global_store_dwordx4 v[68:69], v[160:163], off sc1
	v_mul_f32_e32 v116, v116, v155
	v_mul_f32_e32 v117, v117, v155
	v_mul_f32_e32 v118, v118, v155
	v_mul_f32_e32 v119, v119, v155
	v_mul_f32_e32 v112, v112, v155
	v_mul_f32_e32 v113, v113, v155
	v_mul_f32_e32 v114, v114, v155
	v_mul_f32_e32 v115, v115, v155
	v_mul_f32_e32 v116, v116, v144
	v_mul_f32_e32 v117, v117, v148
	v_mul_f32_e32 v118, v118, v145
	v_mul_f32_e32 v119, v119, v149
	v_mul_f32_e32 v112, v112, v146
	v_mul_f32_e32 v113, v113, v150
	v_mul_f32_e32 v114, v114, v147
	v_mul_f32_e32 v115, v115, v151
	v_mul_f32_e32 v174, v117, v80
	v_mul_f32_e32 v175, v117, v76
	v_mul_f32_e32 v176, v119, v81
	v_mul_f32_e32 v177, v119, v77
	v_mul_f32_e32 v178, v113, v82
	v_mul_f32_e32 v179, v113, v78
	v_mul_f32_e32 v180, v115, v83
	v_mul_f32_e32 v181, v115, v79
	v_fma_f32 v174, v116, v76, -v174
	v_fma_f32 v175, v116, v80, v175
	v_fma_f32 v176, v118, v77, -v176
	v_fma_f32 v177, v118, v81, v177
	v_fma_f32 v178, v112, v78, -v178
	v_fma_f32 v179, v112, v82, v179
	v_fma_f32 v180, v114, v79, -v180
	v_fma_f32 v181, v114, v83, v181
	v_cvt_pk_bf16_f32 v182, v174, v175
	v_cvt_pk_bf16_f32 v183, v176, v177
	v_cvt_pk_bf16_f32 v184, v178, v179
	v_cvt_pk_bf16_f32 v185, v180, v181
	global_store_dwordx4 v[68:69], v[182:185], off offset:256 sc1
	v_add_u32_e32 v200, 32, v70
	v_and_b32_e32 v200, 0x1fff, v200
	v_and_b32_e32 v201, 63, v200
	v_lshrrev_b32_e32 v200, 6, v200
	s_cmp_gt_u32 s59, 1
	s_cselect_b64 vcc, -1, 0
	v_cndmask_b32_e32 v200, v200, v201, vcc
	v_cvt_f32_u32_e32 v200, v200
	v_mul_f32_e32 v76, v200, v84
	v_mul_f32_e32 v77, v200, v85
	v_mul_f32_e32 v78, v200, v86
	v_mul_f32_e32 v79, v200, v87
	v_mul_f32_e32 v76, 0.15915494, v76
	v_mul_f32_e32 v77, 0.15915494, v77
	v_mul_f32_e32 v78, 0.15915494, v78
	v_mul_f32_e32 v79, 0.15915494, v79
	v_sin_f32_e32 v80, v76
	v_sin_f32_e32 v81, v77
	v_sin_f32_e32 v82, v78
	v_sin_f32_e32 v83, v79
	v_cos_f32_e32 v76, v76
	v_cos_f32_e32 v77, v77
	v_cos_f32_e32 v78, v78
	v_cos_f32_e32 v79, v79
	s_cmp_lg_u32 s74, 0
	s_cselect_b64 vcc, -1, 0
	v_cndmask_b32_e64 v76, v76, 1.0, vcc
;     __device__ __forceinline__ void operator()(f32x4 (&acc)[2][2][4][2], const Unit& u, int wr, int wc, int fr, int fq) const {
;     ...
; #pragma unroll
;         for (int ai = 0; ai < 2; ++ai)
; #pragma unroll
;             for (int m = 0; m < 4; ++m) { const int rl = wr * 64 + fr + ai * HALF + m * 16, row = rowt + rl;
;                 int kvrow; float cs[2][2], sn[2][2];
;                 if (is_lat) { const int t = row & (SEQ - 1); kvrow = b * SKV + CTXL + t; const float pos = (float)((wc >> 1) ? (t & 63) : (t >> 6));
; #pragma unroll
;                     for (int n = 0; n < 2; ++n)
; #pragma unroll
;                         for (int pr = 0; pr < 2; ++pr) { const float a = pos * inv[n][pr]; cs[n][pr] = __cosf(a); sn[n][pr] = __sinf(a); } }
;                 else { kvrow = ((row - MLAT) >> 8) * SKV + ((row - MLAT) & (CTXL - 1));
; #pragma unroll
;                     for (int n = 0; n < 2; ++n)
; #pragma unroll
;                         for (int pr = 0; pr < 2; ++pr) { cs[n][pr] = 1.f; sn[n][pr] = 0.f; } }
; #pragma unroll
;                 for (int bj = 0; bj < 2; ++bj) { f32x4 v0 = acc[ai][bj][m][0], v1 = acc[ai][bj][m][1]; bf16_t* dst;
;                     if (qk) { const f32x4 pt = *(const PG8_LAS f32x4*)(P + (rl * 2 + bj) * 4);
;                         const float hr = rsqrtf(((pt[0] + pt[1]) + (pt[2] + pt[3])) * (1.f / 128.f) + EPS);
; #pragma unroll
;                         for (int e = 0; e < 4; ++e) { v0[e] = v0[e] * hr * gq[0][e]; v1[e] = v1[e] * hr * gq[1][e]; }
;                         const f32x4 r0 = {v0[0] * cs[0][0] - v0[1] * sn[0][0], v0[0] * sn[0][0] + v0[1] * cs[0][0], v0[2] * cs[0][1] - v0[3] * sn[0][1], v0[2] * sn[0][1] + v0[3] * cs[0][1]};
;                         const f32x4 r1 = {v1[0] * cs[1][0] - v1[1] * sn[1][0], v1[0] * sn[1][0] + v1[1] * cs[1][0], v1[2] * cs[1][1] - v1[3] * sn[1][1], v1[2] * sn[1][1] + v1[3] * cs[1][1]};
;                         v0 = r0; v1 = r1;
;                         dst = u.pn < 4 ? Q + (size_t)row * DM + (u.pn * 2 + bj) * 128 : K + (size_t)kvrow * 512 + ((u.pn - 4) * 2 + bj) * 128;
;                     } else dst = V + (size_t)kvrow * 512 + ((u.pn - 6) * 2 + bj) * 128;
;                     u32x4 w; w.x = cvt_pk_bf16(v0[0], v0[1]); w.y = cvt_pk_bf16(v0[2], v0[3]); w.z = cvt_pk_bf16(v1[0], v1[1]); w.w = cvt_pk_bf16(v1[2], v1[3]);
;                     *(u32x4*)(dst + wc * 32 + 8 * fq) = w; } }
	v_cndmask_b32_e64 v80, v80, 0, vcc
	v_cndmask_b32_e64 v77, v77, 1.0, vcc
	v_cndmask_b32_e64 v81, v81, 0, vcc
	v_cndmask_b32_e64 v78, v78, 1.0, vcc
	v_cndmask_b32_e64 v82, v82, 0, vcc
	v_cndmask_b32_e64 v79, v79, 1.0, vcc
	v_cndmask_b32_e64 v83, v83, 0, vcc
	v_lshl_add_u64 v[68:69], v[68:69], 0, s[76:77]
	v_mul_f32_e32 v108, v108, v156
	v_mul_f32_e32 v109, v109, v156
	v_mul_f32_e32 v110, v110, v156
	v_mul_f32_e32 v111, v111, v156
	v_mul_f32_e32 v104, v104, v156
	v_mul_f32_e32 v105, v105, v156
	v_mul_f32_e32 v106, v106, v156
	v_mul_f32_e32 v107, v107, v156
	v_mul_f32_e32 v108, v108, v144
	v_mul_f32_e32 v109, v109, v148
	v_mul_f32_e32 v110, v110, v145
	v_mul_f32_e32 v111, v111, v149
	v_mul_f32_e32 v104, v104, v146
	v_mul_f32_e32 v105, v105, v150
	v_mul_f32_e32 v106, v106, v147
	v_mul_f32_e32 v107, v107, v151
	v_mul_f32_e32 v174, v109, v80
	v_mul_f32_e32 v175, v109, v76
	v_mul_f32_e32 v176, v111, v81
	v_mul_f32_e32 v177, v111, v77
	v_mul_f32_e32 v178, v105, v82
	v_mul_f32_e32 v179, v105, v78
	v_mul_f32_e32 v180, v107, v83
	v_mul_f32_e32 v181, v107, v79
	v_fma_f32 v174, v108, v76, -v174
	v_fma_f32 v175, v108, v80, v175
	v_fma_f32 v176, v110, v77, -v176
	v_fma_f32 v177, v110, v81, v177
	v_fma_f32 v178, v104, v78, -v178
	v_fma_f32 v179, v104, v82, v179
	v_fma_f32 v180, v106, v79, -v180
	v_fma_f32 v181, v106, v83, v181
	v_cvt_pk_bf16_f32 v160, v174, v175
	v_cvt_pk_bf16_f32 v161, v176, v177
	v_cvt_pk_bf16_f32 v162, v178, v179
	v_cvt_pk_bf16_f32 v163, v180, v181
	global_store_dwordx4 v[68:69], v[160:163], off sc1
	v_mul_f32_e32 v100, v100, v157
	v_mul_f32_e32 v101, v101, v157
	v_mul_f32_e32 v102, v102, v157
	v_mul_f32_e32 v103, v103, v157
	v_mul_f32_e32 v96, v96, v157
	v_mul_f32_e32 v97, v97, v157
	v_mul_f32_e32 v98, v98, v157
	v_mul_f32_e32 v99, v99, v157
	v_mul_f32_e32 v100, v100, v144
	v_mul_f32_e32 v101, v101, v148
	v_mul_f32_e32 v102, v102, v145
	v_mul_f32_e32 v103, v103, v149
	v_mul_f32_e32 v96, v96, v146
	v_mul_f32_e32 v97, v97, v150
	v_mul_f32_e32 v98, v98, v147
	v_mul_f32_e32 v99, v99, v151
	v_mul_f32_e32 v174, v101, v80
	v_mul_f32_e32 v175, v101, v76
	v_mul_f32_e32 v176, v103, v81
	v_mul_f32_e32 v177, v103, v77
	v_mul_f32_e32 v178, v97, v82
	v_mul_f32_e32 v179, v97, v78
	v_mul_f32_e32 v180, v99, v83
	v_mul_f32_e32 v181, v99, v79
	v_fma_f32 v174, v100, v76, -v174
	v_fma_f32 v175, v100, v80, v175
	v_fma_f32 v176, v102, v77, -v176
	v_fma_f32 v177, v102, v81, v177
	v_fma_f32 v178, v96, v78, -v178
	v_fma_f32 v179, v96, v82, v179
	v_fma_f32 v180, v98, v79, -v180
	v_fma_f32 v181, v98, v83, v181
	v_cvt_pk_bf16_f32 v182, v174, v175
	v_cvt_pk_bf16_f32 v183, v176, v177
	v_cvt_pk_bf16_f32 v184, v178, v179
	v_cvt_pk_bf16_f32 v185, v180, v181
	global_store_dwordx4 v[68:69], v[182:185], off offset:256 sc1
	v_add_u32_e32 v200, 48, v70
	v_and_b32_e32 v200, 0x1fff, v200
	v_and_b32_e32 v201, 63, v200
	v_lshrrev_b32_e32 v200, 6, v200
	s_cmp_gt_u32 s59, 1
	s_cselect_b64 vcc, -1, 0
	v_cndmask_b32_e32 v200, v200, v201, vcc
	v_cvt_f32_u32_e32 v200, v200
	v_mul_f32_e32 v76, v200, v84
	v_mul_f32_e32 v77, v200, v85
	v_mul_f32_e32 v78, v200, v86
	v_mul_f32_e32 v79, v200, v87
	v_mul_f32_e32 v76, 0.15915494, v76
	v_mul_f32_e32 v77, 0.15915494, v77
	v_mul_f32_e32 v78, 0.15915494, v78
	v_mul_f32_e32 v79, 0.15915494, v79
	v_sin_f32_e32 v80, v76
	v_sin_f32_e32 v81, v77
	v_sin_f32_e32 v82, v78
	v_sin_f32_e32 v83, v79
	v_cos_f32_e32 v76, v76
	v_cos_f32_e32 v77, v77
	v_cos_f32_e32 v78, v78
	v_cos_f32_e32 v79, v79
	s_cmp_lg_u32 s74, 0
	s_cselect_b64 vcc, -1, 0
	v_cndmask_b32_e64 v76, v76, 1.0, vcc
	v_cndmask_b32_e64 v80, v80, 0, vcc
	v_cndmask_b32_e64 v77, v77, 1.0, vcc
	v_cndmask_b32_e64 v81, v81, 0, vcc
	v_cndmask_b32_e64 v78, v78, 1.0, vcc
	v_cndmask_b32_e64 v82, v82, 0, vcc
	v_cndmask_b32_e64 v79, v79, 1.0, vcc
	v_cndmask_b32_e64 v83, v83, 0, vcc
	v_lshl_add_u64 v[68:69], v[68:69], 0, s[76:77]
	v_mul_f32_e32 v92, v92, v158
	v_mul_f32_e32 v93, v93, v158
	v_mul_f32_e32 v94, v94, v158
	v_mul_f32_e32 v95, v95, v158
	v_mul_f32_e32 v88, v88, v158
	v_mul_f32_e32 v89, v89, v158
	v_mul_f32_e32 v90, v90, v158
	v_mul_f32_e32 v91, v91, v158
	v_mul_f32_e32 v92, v92, v144
	v_mul_f32_e32 v93, v93, v148
	v_mul_f32_e32 v94, v94, v145
	v_mul_f32_e32 v95, v95, v149
	v_mul_f32_e32 v88, v88, v146
	v_mul_f32_e32 v89, v89, v150
	v_mul_f32_e32 v90, v90, v147
	v_mul_f32_e32 v91, v91, v151
	v_mul_f32_e32 v174, v93, v80
	v_mul_f32_e32 v175, v93, v76
	v_mul_f32_e32 v176, v95, v81
	v_mul_f32_e32 v177, v95, v77
	v_mul_f32_e32 v178, v89, v82
	v_mul_f32_e32 v179, v89, v78
	v_mul_f32_e32 v180, v91, v83
	v_mul_f32_e32 v181, v91, v79
	v_fma_f32 v174, v92, v76, -v174
	v_fma_f32 v175, v92, v80, v175
	v_fma_f32 v176, v94, v77, -v176
	v_fma_f32 v177, v94, v81, v177
	v_fma_f32 v178, v88, v78, -v178
	v_fma_f32 v179, v88, v82, v179
	v_fma_f32 v180, v90, v79, -v180
	v_fma_f32 v181, v90, v83, v181
	v_cvt_pk_bf16_f32 v160, v174, v175
	v_cvt_pk_bf16_f32 v161, v176, v177
	v_cvt_pk_bf16_f32 v162, v178, v179
	v_cvt_pk_bf16_f32 v163, v180, v181
	global_store_dwordx4 v[68:69], v[160:163], off sc1
	v_mul_f32_e32 v72, v72, v159
	v_mul_f32_e32 v73, v73, v159
	v_mul_f32_e32 v74, v74, v159
	v_mul_f32_e32 v75, v75, v159
	v_mul_f32_e32 v64, v64, v159
	v_mul_f32_e32 v65, v65, v159
	v_mul_f32_e32 v66, v66, v159
	v_mul_f32_e32 v67, v67, v159
	v_mul_f32_e32 v72, v72, v144
	v_mul_f32_e32 v73, v73, v148
	v_mul_f32_e32 v74, v74, v145
	v_mul_f32_e32 v75, v75, v149
	v_mul_f32_e32 v64, v64, v146
	v_mul_f32_e32 v65, v65, v150
	v_mul_f32_e32 v66, v66, v147
	v_mul_f32_e32 v67, v67, v151
	v_mul_f32_e32 v174, v73, v80
	v_mul_f32_e32 v175, v73, v76
	v_mul_f32_e32 v176, v75, v81
	v_mul_f32_e32 v177, v75, v77
	v_mul_f32_e32 v178, v65, v82
;     __device__ __forceinline__ void operator()(f32x4 (&acc)[2][2][4][2], const Unit& u, int wr, int wc, int fr, int fq) const {
;     ...
; #pragma unroll
;         for (int ai = 0; ai < 2; ++ai)
; #pragma unroll
;             for (int m = 0; m < 4; ++m) { const int rl = wr * 64 + fr + ai * HALF + m * 16, row = rowt + rl;
;                 int kvrow; float cs[2][2], sn[2][2];
;                 if (is_lat) { const int t = row & (SEQ - 1); kvrow = b * SKV + CTXL + t; const float pos = (float)((wc >> 1) ? (t & 63) : (t >> 6));
; #pragma unroll
;                     for (int n = 0; n < 2; ++n)
; #pragma unroll
;                         for (int pr = 0; pr < 2; ++pr) { const float a = pos * inv[n][pr]; cs[n][pr] = __cosf(a); sn[n][pr] = __sinf(a); } }
;                 else { kvrow = ((row - MLAT) >> 8) * SKV + ((row - MLAT) & (CTXL - 1));
; #pragma unroll
;                     for (int n = 0; n < 2; ++n)
; #pragma unroll
;                         for (int pr = 0; pr < 2; ++pr) { cs[n][pr] = 1.f; sn[n][pr] = 0.f; } }
; #pragma unroll
;                 for (int bj = 0; bj < 2; ++bj) { f32x4 v0 = acc[ai][bj][m][0], v1 = acc[ai][bj][m][1]; bf16_t* dst;
;                     if (qk) { const f32x4 pt = *(const PG8_LAS f32x4*)(P + (rl * 2 + bj) * 4);
;                         const float hr = rsqrtf(((pt[0] + pt[1]) + (pt[2] + pt[3])) * (1.f / 128.f) + EPS);
; #pragma unroll
;                         for (int e = 0; e < 4; ++e) { v0[e] = v0[e] * hr * gq[0][e]; v1[e] = v1[e] * hr * gq[1][e]; }
;                         const f32x4 r0 = {v0[0] * cs[0][0] - v0[1] * sn[0][0], v0[0] * sn[0][0] + v0[1] * cs[0][0], v0[2] * cs[0][1] - v0[3] * sn[0][1], v0[2] * sn[0][1] + v0[3] * cs[0][1]};
;                         const f32x4 r1 = {v1[0] * cs[1][0] - v1[1] * sn[1][0], v1[0] * sn[1][0] + v1[1] * cs[1][0], v1[2] * cs[1][1] - v1[3] * sn[1][1], v1[2] * sn[1][1] + v1[3] * cs[1][1]};
;                         v0 = r0; v1 = r1;
;                         dst = u.pn < 4 ? Q + (size_t)row * DM + (u.pn * 2 + bj) * 128 : K + (size_t)kvrow * 512 + ((u.pn - 4) * 2 + bj) * 128;
;                     } else dst = V + (size_t)kvrow * 512 + ((u.pn - 6) * 2 + bj) * 128;
;                     u32x4 w; w.x = cvt_pk_bf16(v0[0], v0[1]); w.y = cvt_pk_bf16(v0[2], v0[3]); w.z = cvt_pk_bf16(v1[0], v1[1]); w.w = cvt_pk_bf16(v1[2], v1[3]);
;                     *(u32x4*)(dst + wc * 32 + 8 * fq) = w; } }
	v_mul_f32_e32 v179, v65, v78
	v_mul_f32_e32 v180, v67, v83
	v_mul_f32_e32 v181, v67, v79
	v_fma_f32 v174, v72, v76, -v174
	v_fma_f32 v175, v72, v80, v175
	v_fma_f32 v176, v74, v77, -v176
	v_fma_f32 v177, v74, v81, v177
	v_fma_f32 v178, v64, v78, -v178
	v_fma_f32 v179, v64, v82, v179
	v_fma_f32 v180, v66, v79, -v180
	v_fma_f32 v181, v66, v83, v181
	v_cvt_pk_bf16_f32 v182, v174, v175
	v_cvt_pk_bf16_f32 v183, v176, v177
	v_cvt_pk_bf16_f32 v184, v178, v179
	v_cvt_pk_bf16_f32 v185, v180, v181
	global_store_dwordx4 v[68:69], v[182:185], off offset:256 sc1
	v_add_u32_e32 v200, 128, v70
	v_and_b32_e32 v200, 0x1fff, v200
	v_and_b32_e32 v201, 63, v200
	v_lshrrev_b32_e32 v200, 6, v200
	s_cmp_gt_u32 s59, 1
	s_cselect_b64 vcc, -1, 0
	v_cndmask_b32_e32 v200, v200, v201, vcc
	v_cvt_f32_u32_e32 v200, v200
	v_mul_f32_e32 v76, v200, v84
	v_mul_f32_e32 v77, v200, v85
	v_mul_f32_e32 v78, v200, v86
	v_mul_f32_e32 v79, v200, v87
	v_mul_f32_e32 v76, 0.15915494, v76
	v_mul_f32_e32 v77, 0.15915494, v77
	v_mul_f32_e32 v78, 0.15915494, v78
	v_mul_f32_e32 v79, 0.15915494, v79
	v_sin_f32_e32 v80, v76
	v_sin_f32_e32 v81, v77
	v_sin_f32_e32 v82, v78
	v_sin_f32_e32 v83, v79
	v_cos_f32_e32 v76, v76
	v_cos_f32_e32 v77, v77
	v_cos_f32_e32 v78, v78
	v_cos_f32_e32 v79, v79
	s_cmp_lg_u32 s74, 0
	s_cselect_b64 vcc, -1, 0
	v_cndmask_b32_e64 v76, v76, 1.0, vcc
	v_cndmask_b32_e64 v80, v80, 0, vcc
	v_cndmask_b32_e64 v77, v77, 1.0, vcc
	v_cndmask_b32_e64 v81, v81, 0, vcc
	v_cndmask_b32_e64 v78, v78, 1.0, vcc
	v_cndmask_b32_e64 v82, v82, 0, vcc
	v_cndmask_b32_e64 v79, v79, 1.0, vcc
	v_cndmask_b32_e64 v83, v83, 0, vcc
	v_lshl_add_u64 v[68:69], v[68:69], 0, s[78:79]
	v_mul_f32_e32 v60, v60, v191
	v_mul_f32_e32 v61, v61, v191
	v_mul_f32_e32 v62, v62, v191
	v_mul_f32_e32 v63, v63, v191
	v_mul_f32_e32 v56, v56, v191
	v_mul_f32_e32 v57, v57, v191
	v_mul_f32_e32 v58, v58, v191
	v_mul_f32_e32 v59, v59, v191
	v_mul_f32_e32 v60, v60, v144
	v_mul_f32_e32 v61, v61, v148
	v_mul_f32_e32 v62, v62, v145
	v_mul_f32_e32 v63, v63, v149
	v_mul_f32_e32 v56, v56, v146
	v_mul_f32_e32 v57, v57, v150
	v_mul_f32_e32 v58, v58, v147
	v_mul_f32_e32 v59, v59, v151
	v_mul_f32_e32 v174, v61, v80
	v_mul_f32_e32 v175, v61, v76
	v_mul_f32_e32 v176, v63, v81
	v_mul_f32_e32 v177, v63, v77
	v_mul_f32_e32 v178, v57, v82
	v_mul_f32_e32 v179, v57, v78
	v_mul_f32_e32 v180, v59, v83
	v_mul_f32_e32 v181, v59, v79
	v_fma_f32 v174, v60, v76, -v174
	v_fma_f32 v175, v60, v80, v175
	v_fma_f32 v176, v62, v77, -v176
	v_fma_f32 v177, v62, v81, v177
	v_fma_f32 v178, v56, v78, -v178
	v_fma_f32 v179, v56, v82, v179
	v_fma_f32 v180, v58, v79, -v180
	v_fma_f32 v181, v58, v83, v181
	v_cvt_pk_bf16_f32 v160, v174, v175
	v_cvt_pk_bf16_f32 v161, v176, v177
	v_cvt_pk_bf16_f32 v162, v178, v179
	v_cvt_pk_bf16_f32 v163, v180, v181
	global_store_dwordx4 v[68:69], v[160:163], off sc1
	v_mul_f32_e32 v52, v52, v192
	v_mul_f32_e32 v53, v53, v192
	v_mul_f32_e32 v54, v54, v192
	v_mul_f32_e32 v55, v55, v192
	v_mul_f32_e32 v48, v48, v192
	v_mul_f32_e32 v49, v49, v192
	v_mul_f32_e32 v50, v50, v192
	v_mul_f32_e32 v51, v51, v192
	v_mul_f32_e32 v52, v52, v144
	v_mul_f32_e32 v53, v53, v148
	v_mul_f32_e32 v54, v54, v145
	v_mul_f32_e32 v55, v55, v149
	v_mul_f32_e32 v48, v48, v146
	v_mul_f32_e32 v49, v49, v150
	v_mul_f32_e32 v50, v50, v147
	v_mul_f32_e32 v51, v51, v151
	v_mul_f32_e32 v174, v53, v80
	v_mul_f32_e32 v175, v53, v76
	v_mul_f32_e32 v176, v55, v81
	v_mul_f32_e32 v177, v55, v77
	v_mul_f32_e32 v178, v49, v82
	v_mul_f32_e32 v179, v49, v78
	v_mul_f32_e32 v180, v51, v83
	v_mul_f32_e32 v181, v51, v79
	v_fma_f32 v174, v52, v76, -v174
	v_fma_f32 v175, v52, v80, v175
	v_fma_f32 v176, v54, v77, -v176
	v_fma_f32 v177, v54, v81, v177
	v_fma_f32 v178, v48, v78, -v178
	v_fma_f32 v179, v48, v82, v179
	v_fma_f32 v180, v50, v79, -v180
	v_fma_f32 v181, v50, v83, v181
	v_cvt_pk_bf16_f32 v182, v174, v175
	v_cvt_pk_bf16_f32 v183, v176, v177
	v_cvt_pk_bf16_f32 v184, v178, v179
	v_cvt_pk_bf16_f32 v185, v180, v181
	global_store_dwordx4 v[68:69], v[182:185], off offset:256 sc1
	v_add_u32_e32 v200, 144, v70
	v_and_b32_e32 v200, 0x1fff, v200
	v_and_b32_e32 v201, 63, v200
	v_lshrrev_b32_e32 v200, 6, v200
	s_cmp_gt_u32 s59, 1
	s_cselect_b64 vcc, -1, 0
	v_cndmask_b32_e32 v200, v200, v201, vcc
	v_cvt_f32_u32_e32 v200, v200
	v_mul_f32_e32 v76, v200, v84
	v_mul_f32_e32 v77, v200, v85
	v_mul_f32_e32 v78, v200, v86
	v_mul_f32_e32 v79, v200, v87
	v_mul_f32_e32 v76, 0.15915494, v76
	v_mul_f32_e32 v77, 0.15915494, v77
	v_mul_f32_e32 v78, 0.15915494, v78
	v_mul_f32_e32 v79, 0.15915494, v79
	v_sin_f32_e32 v80, v76
	v_sin_f32_e32 v81, v77
	v_sin_f32_e32 v82, v78
	v_sin_f32_e32 v83, v79
	v_cos_f32_e32 v76, v76
	v_cos_f32_e32 v77, v77
	v_cos_f32_e32 v78, v78
	v_cos_f32_e32 v79, v79
	s_cmp_lg_u32 s74, 0
	s_cselect_b64 vcc, -1, 0
	v_cndmask_b32_e64 v76, v76, 1.0, vcc
	v_cndmask_b32_e64 v80, v80, 0, vcc
	v_cndmask_b32_e64 v77, v77, 1.0, vcc
	v_cndmask_b32_e64 v81, v81, 0, vcc
	v_cndmask_b32_e64 v78, v78, 1.0, vcc
	v_cndmask_b32_e64 v82, v82, 0, vcc
	v_cndmask_b32_e64 v79, v79, 1.0, vcc
	v_cndmask_b32_e64 v83, v83, 0, vcc
	v_lshl_add_u64 v[68:69], v[68:69], 0, s[76:77]
	v_mul_f32_e32 v44, v44, v193
	v_mul_f32_e32 v45, v45, v193
	v_mul_f32_e32 v46, v46, v193
	v_mul_f32_e32 v47, v47, v193
	v_mul_f32_e32 v40, v40, v193
	v_mul_f32_e32 v41, v41, v193
	v_mul_f32_e32 v42, v42, v193
	v_mul_f32_e32 v43, v43, v193
	v_mul_f32_e32 v44, v44, v144
	v_mul_f32_e32 v45, v45, v148
	v_mul_f32_e32 v46, v46, v145
	v_mul_f32_e32 v47, v47, v149
	v_mul_f32_e32 v40, v40, v146
	v_mul_f32_e32 v41, v41, v150
	v_mul_f32_e32 v42, v42, v147
	v_mul_f32_e32 v43, v43, v151
	v_mul_f32_e32 v174, v45, v80
	v_mul_f32_e32 v175, v45, v76
;     __device__ __forceinline__ void operator()(f32x4 (&acc)[2][2][4][2], const Unit& u, int wr, int wc, int fr, int fq) const {
;     ...
; #pragma unroll
;         for (int ai = 0; ai < 2; ++ai)
; #pragma unroll
;             for (int m = 0; m < 4; ++m) { const int rl = wr * 64 + fr + ai * HALF + m * 16, row = rowt + rl;
;                 int kvrow; float cs[2][2], sn[2][2];
;                 if (is_lat) { const int t = row & (SEQ - 1); kvrow = b * SKV + CTXL + t; const float pos = (float)((wc >> 1) ? (t & 63) : (t >> 6));
; #pragma unroll
;                     for (int n = 0; n < 2; ++n)
; #pragma unroll
;                         for (int pr = 0; pr < 2; ++pr) { const float a = pos * inv[n][pr]; cs[n][pr] = __cosf(a); sn[n][pr] = __sinf(a); } }
;                 else { kvrow = ((row - MLAT) >> 8) * SKV + ((row - MLAT) & (CTXL - 1));
; #pragma unroll
;                     for (int n = 0; n < 2; ++n)
; #pragma unroll
;                         for (int pr = 0; pr < 2; ++pr) { cs[n][pr] = 1.f; sn[n][pr] = 0.f; } }
; #pragma unroll
;                 for (int bj = 0; bj < 2; ++bj) { f32x4 v0 = acc[ai][bj][m][0], v1 = acc[ai][bj][m][1]; bf16_t* dst;
;                     if (qk) { const f32x4 pt = *(const PG8_LAS f32x4*)(P + (rl * 2 + bj) * 4);
;                         const float hr = rsqrtf(((pt[0] + pt[1]) + (pt[2] + pt[3])) * (1.f / 128.f) + EPS);
; #pragma unroll
;                         for (int e = 0; e < 4; ++e) { v0[e] = v0[e] * hr * gq[0][e]; v1[e] = v1[e] * hr * gq[1][e]; }
;                         const f32x4 r0 = {v0[0] * cs[0][0] - v0[1] * sn[0][0], v0[0] * sn[0][0] + v0[1] * cs[0][0], v0[2] * cs[0][1] - v0[3] * sn[0][1], v0[2] * sn[0][1] + v0[3] * cs[0][1]};
;                         const f32x4 r1 = {v1[0] * cs[1][0] - v1[1] * sn[1][0], v1[0] * sn[1][0] + v1[1] * cs[1][0], v1[2] * cs[1][1] - v1[3] * sn[1][1], v1[2] * sn[1][1] + v1[3] * cs[1][1]};
;                         v0 = r0; v1 = r1;
;                         dst = u.pn < 4 ? Q + (size_t)row * DM + (u.pn * 2 + bj) * 128 : K + (size_t)kvrow * 512 + ((u.pn - 4) * 2 + bj) * 128;
;                     } else dst = V + (size_t)kvrow * 512 + ((u.pn - 6) * 2 + bj) * 128;
;                     u32x4 w; w.x = cvt_pk_bf16(v0[0], v0[1]); w.y = cvt_pk_bf16(v0[2], v0[3]); w.z = cvt_pk_bf16(v1[0], v1[1]); w.w = cvt_pk_bf16(v1[2], v1[3]);
;                     *(u32x4*)(dst + wc * 32 + 8 * fq) = w; } }
	v_mul_f32_e32 v176, v47, v81
	v_mul_f32_e32 v177, v47, v77
	v_mul_f32_e32 v178, v41, v82
	v_mul_f32_e32 v179, v41, v78
	v_mul_f32_e32 v180, v43, v83
	v_mul_f32_e32 v181, v43, v79
	v_fma_f32 v174, v44, v76, -v174
	v_fma_f32 v175, v44, v80, v175
	v_fma_f32 v176, v46, v77, -v176
	v_fma_f32 v177, v46, v81, v177
	v_fma_f32 v178, v40, v78, -v178
	v_fma_f32 v179, v40, v82, v179
	v_fma_f32 v180, v42, v79, -v180
	v_fma_f32 v181, v42, v83, v181
	v_cvt_pk_bf16_f32 v160, v174, v175
	v_cvt_pk_bf16_f32 v161, v176, v177
	v_cvt_pk_bf16_f32 v162, v178, v179
	v_cvt_pk_bf16_f32 v163, v180, v181
	global_store_dwordx4 v[68:69], v[160:163], off sc1
	v_mul_f32_e32 v36, v36, v194
	v_mul_f32_e32 v37, v37, v194
	v_mul_f32_e32 v38, v38, v194
	v_mul_f32_e32 v39, v39, v194
	v_mul_f32_e32 v32, v32, v194
	v_mul_f32_e32 v33, v33, v194
	v_mul_f32_e32 v34, v34, v194
	v_mul_f32_e32 v35, v35, v194
	v_mul_f32_e32 v36, v36, v144
	v_mul_f32_e32 v37, v37, v148
	v_mul_f32_e32 v38, v38, v145
	v_mul_f32_e32 v39, v39, v149
	v_mul_f32_e32 v32, v32, v146
	v_mul_f32_e32 v33, v33, v150
	v_mul_f32_e32 v34, v34, v147
	v_mul_f32_e32 v35, v35, v151
	v_mul_f32_e32 v174, v37, v80
	v_mul_f32_e32 v175, v37, v76
	v_mul_f32_e32 v176, v39, v81
	v_mul_f32_e32 v177, v39, v77
	v_mul_f32_e32 v178, v33, v82
	v_mul_f32_e32 v179, v33, v78
	v_mul_f32_e32 v180, v35, v83
	v_mul_f32_e32 v181, v35, v79
	v_fma_f32 v174, v36, v76, -v174
	v_fma_f32 v175, v36, v80, v175
	v_fma_f32 v176, v38, v77, -v176
	v_fma_f32 v177, v38, v81, v177
	v_fma_f32 v178, v32, v78, -v178
	v_fma_f32 v179, v32, v82, v179
	v_fma_f32 v180, v34, v79, -v180
	v_fma_f32 v181, v34, v83, v181
	v_cvt_pk_bf16_f32 v182, v174, v175
	v_cvt_pk_bf16_f32 v183, v176, v177
	v_cvt_pk_bf16_f32 v184, v178, v179
	v_cvt_pk_bf16_f32 v185, v180, v181
	global_store_dwordx4 v[68:69], v[182:185], off offset:256 sc1
	v_add_u32_e32 v200, 160, v70
	v_and_b32_e32 v200, 0x1fff, v200
	v_and_b32_e32 v201, 63, v200
	v_lshrrev_b32_e32 v200, 6, v200
	s_cmp_gt_u32 s59, 1
	s_cselect_b64 vcc, -1, 0
	v_cndmask_b32_e32 v200, v200, v201, vcc
	v_cvt_f32_u32_e32 v200, v200
	v_mul_f32_e32 v76, v200, v84
	v_mul_f32_e32 v77, v200, v85
	v_mul_f32_e32 v78, v200, v86
	v_mul_f32_e32 v79, v200, v87
	v_mul_f32_e32 v76, 0.15915494, v76
	v_mul_f32_e32 v77, 0.15915494, v77
	v_mul_f32_e32 v78, 0.15915494, v78
	v_mul_f32_e32 v79, 0.15915494, v79
	v_sin_f32_e32 v80, v76
	v_sin_f32_e32 v81, v77
	v_sin_f32_e32 v82, v78
	v_sin_f32_e32 v83, v79
	v_cos_f32_e32 v76, v76
	v_cos_f32_e32 v77, v77
	v_cos_f32_e32 v78, v78
	v_cos_f32_e32 v79, v79
	s_cmp_lg_u32 s74, 0
	s_cselect_b64 vcc, -1, 0
	v_cndmask_b32_e64 v76, v76, 1.0, vcc
	v_cndmask_b32_e64 v80, v80, 0, vcc
	v_cndmask_b32_e64 v77, v77, 1.0, vcc
	v_cndmask_b32_e64 v81, v81, 0, vcc
	v_cndmask_b32_e64 v78, v78, 1.0, vcc
	v_cndmask_b32_e64 v82, v82, 0, vcc
	v_cndmask_b32_e64 v79, v79, 1.0, vcc
	v_cndmask_b32_e64 v83, v83, 0, vcc
	v_lshl_add_u64 v[68:69], v[68:69], 0, s[76:77]
	v_mul_f32_e32 v28, v28, v195
	v_mul_f32_e32 v29, v29, v195
	v_mul_f32_e32 v30, v30, v195
	v_mul_f32_e32 v31, v31, v195
	v_mul_f32_e32 v24, v24, v195
	v_mul_f32_e32 v25, v25, v195
	v_mul_f32_e32 v26, v26, v195
	v_mul_f32_e32 v27, v27, v195
	v_mul_f32_e32 v28, v28, v144
	v_mul_f32_e32 v29, v29, v148
	v_mul_f32_e32 v30, v30, v145
	v_mul_f32_e32 v31, v31, v149
	v_mul_f32_e32 v24, v24, v146
	v_mul_f32_e32 v25, v25, v150
	v_mul_f32_e32 v26, v26, v147
	v_mul_f32_e32 v27, v27, v151
	v_mul_f32_e32 v174, v29, v80
	v_mul_f32_e32 v175, v29, v76
	v_mul_f32_e32 v176, v31, v81
	v_mul_f32_e32 v177, v31, v77
	v_mul_f32_e32 v178, v25, v82
	v_mul_f32_e32 v179, v25, v78
	v_mul_f32_e32 v180, v27, v83
	v_mul_f32_e32 v181, v27, v79
	v_fma_f32 v174, v28, v76, -v174
	v_fma_f32 v175, v28, v80, v175
	v_fma_f32 v176, v30, v77, -v176
	v_fma_f32 v177, v30, v81, v177
	v_fma_f32 v178, v24, v78, -v178
	v_fma_f32 v179, v24, v82, v179
	v_fma_f32 v180, v26, v79, -v180
	v_fma_f32 v181, v26, v83, v181
	v_cvt_pk_bf16_f32 v160, v174, v175
	v_cvt_pk_bf16_f32 v161, v176, v177
	v_cvt_pk_bf16_f32 v162, v178, v179
	v_cvt_pk_bf16_f32 v163, v180, v181
	global_store_dwordx4 v[68:69], v[160:163], off sc1
	v_mul_f32_e32 v20, v20, v196
	v_mul_f32_e32 v21, v21, v196
	v_mul_f32_e32 v22, v22, v196
	v_mul_f32_e32 v23, v23, v196
	v_mul_f32_e32 v16, v16, v196
	v_mul_f32_e32 v17, v17, v196
	v_mul_f32_e32 v18, v18, v196
	v_mul_f32_e32 v19, v19, v196
	v_mul_f32_e32 v20, v20, v144
	v_mul_f32_e32 v21, v21, v148
	v_mul_f32_e32 v22, v22, v145
	v_mul_f32_e32 v23, v23, v149
	v_mul_f32_e32 v16, v16, v146
	v_mul_f32_e32 v17, v17, v150
	v_mul_f32_e32 v18, v18, v147
	v_mul_f32_e32 v19, v19, v151
	v_mul_f32_e32 v174, v21, v80
	v_mul_f32_e32 v175, v21, v76
	v_mul_f32_e32 v176, v23, v81
	v_mul_f32_e32 v177, v23, v77
	v_mul_f32_e32 v178, v17, v82
	v_mul_f32_e32 v179, v17, v78
	v_mul_f32_e32 v180, v19, v83
	v_mul_f32_e32 v181, v19, v79
	v_fma_f32 v174, v20, v76, -v174
	v_fma_f32 v175, v20, v80, v175
	v_fma_f32 v176, v22, v77, -v176
	v_fma_f32 v177, v22, v81, v177
	v_fma_f32 v178, v16, v78, -v178
	v_fma_f32 v179, v16, v82, v179
	v_fma_f32 v180, v18, v79, -v180
	v_fma_f32 v181, v18, v83, v181
	v_cvt_pk_bf16_f32 v182, v174, v175
	v_cvt_pk_bf16_f32 v183, v176, v177
	v_cvt_pk_bf16_f32 v184, v178, v179
	v_cvt_pk_bf16_f32 v185, v180, v181
	global_store_dwordx4 v[68:69], v[182:185], off offset:256 sc1
	v_add_u32_e32 v200, 176, v70
	v_and_b32_e32 v200, 0x1fff, v200
	v_and_b32_e32 v201, 63, v200
	v_lshrrev_b32_e32 v200, 6, v200
	s_cmp_gt_u32 s59, 1
	s_cselect_b64 vcc, -1, 0
	v_cndmask_b32_e32 v200, v200, v201, vcc
	v_cvt_f32_u32_e32 v200, v200
	v_mul_f32_e32 v76, v200, v84
	v_mul_f32_e32 v77, v200, v85
	v_mul_f32_e32 v78, v200, v86
	v_mul_f32_e32 v79, v200, v87
;     __device__ __forceinline__ void operator()(f32x4 (&acc)[2][2][4][2], const Unit& u, int wr, int wc, int fr, int fq) const {
;     ...
; #pragma unroll
;         for (int ai = 0; ai < 2; ++ai)
; #pragma unroll
;             for (int m = 0; m < 4; ++m) { const int rl = wr * 64 + fr + ai * HALF + m * 16, row = rowt + rl;
;                 int kvrow; float cs[2][2], sn[2][2];
;                 if (is_lat) { const int t = row & (SEQ - 1); kvrow = b * SKV + CTXL + t; const float pos = (float)((wc >> 1) ? (t & 63) : (t >> 6));
; #pragma unroll
;                     for (int n = 0; n < 2; ++n)
; #pragma unroll
;                         for (int pr = 0; pr < 2; ++pr) { const float a = pos * inv[n][pr]; cs[n][pr] = __cosf(a); sn[n][pr] = __sinf(a); } }
;                 else { kvrow = ((row - MLAT) >> 8) * SKV + ((row - MLAT) & (CTXL - 1));
; #pragma unroll
;                     for (int n = 0; n < 2; ++n)
; #pragma unroll
;                         for (int pr = 0; pr < 2; ++pr) { cs[n][pr] = 1.f; sn[n][pr] = 0.f; } }
; #pragma unroll
;                 for (int bj = 0; bj < 2; ++bj) { f32x4 v0 = acc[ai][bj][m][0], v1 = acc[ai][bj][m][1]; bf16_t* dst;
;                     if (qk) { const f32x4 pt = *(const PG8_LAS f32x4*)(P + (rl * 2 + bj) * 4);
;                         const float hr = rsqrtf(((pt[0] + pt[1]) + (pt[2] + pt[3])) * (1.f / 128.f) + EPS);
; #pragma unroll
;                         for (int e = 0; e < 4; ++e) { v0[e] = v0[e] * hr * gq[0][e]; v1[e] = v1[e] * hr * gq[1][e]; }
;                         const f32x4 r0 = {v0[0] * cs[0][0] - v0[1] * sn[0][0], v0[0] * sn[0][0] + v0[1] * cs[0][0], v0[2] * cs[0][1] - v0[3] * sn[0][1], v0[2] * sn[0][1] + v0[3] * cs[0][1]};
;                         const f32x4 r1 = {v1[0] * cs[1][0] - v1[1] * sn[1][0], v1[0] * sn[1][0] + v1[1] * cs[1][0], v1[2] * cs[1][1] - v1[3] * sn[1][1], v1[2] * sn[1][1] + v1[3] * cs[1][1]};
;                         v0 = r0; v1 = r1;
;                         dst = u.pn < 4 ? Q + (size_t)row * DM + (u.pn * 2 + bj) * 128 : K + (size_t)kvrow * 512 + ((u.pn - 4) * 2 + bj) * 128;
;                     } else dst = V + (size_t)kvrow * 512 + ((u.pn - 6) * 2 + bj) * 128;
;                     u32x4 w; w.x = cvt_pk_bf16(v0[0], v0[1]); w.y = cvt_pk_bf16(v0[2], v0[3]); w.z = cvt_pk_bf16(v1[0], v1[1]); w.w = cvt_pk_bf16(v1[2], v1[3]);
;                     *(u32x4*)(dst + wc * 32 + 8 * fq) = w; } }
	v_mul_f32_e32 v76, 0.15915494, v76
	v_mul_f32_e32 v77, 0.15915494, v77
	v_mul_f32_e32 v78, 0.15915494, v78
	v_mul_f32_e32 v79, 0.15915494, v79
	v_sin_f32_e32 v80, v76
	v_sin_f32_e32 v81, v77
	v_sin_f32_e32 v82, v78
	v_sin_f32_e32 v83, v79
	v_cos_f32_e32 v76, v76
	v_cos_f32_e32 v77, v77
	v_cos_f32_e32 v78, v78
	v_cos_f32_e32 v79, v79
	s_cmp_lg_u32 s74, 0
	s_cselect_b64 vcc, -1, 0
	v_cndmask_b32_e64 v76, v76, 1.0, vcc
	v_cndmask_b32_e64 v80, v80, 0, vcc
	v_cndmask_b32_e64 v77, v77, 1.0, vcc
	v_cndmask_b32_e64 v81, v81, 0, vcc
	v_cndmask_b32_e64 v78, v78, 1.0, vcc
	v_cndmask_b32_e64 v82, v82, 0, vcc
	v_cndmask_b32_e64 v79, v79, 1.0, vcc
	v_cndmask_b32_e64 v83, v83, 0, vcc
	v_lshl_add_u64 v[68:69], v[68:69], 0, s[76:77]
	v_mul_f32_e32 v12, v12, v197
	v_mul_f32_e32 v13, v13, v197
	v_mul_f32_e32 v14, v14, v197
	v_mul_f32_e32 v15, v15, v197
	v_mul_f32_e32 v8, v8, v197
	v_mul_f32_e32 v9, v9, v197
	v_mul_f32_e32 v10, v10, v197
	v_mul_f32_e32 v11, v11, v197
	v_mul_f32_e32 v12, v12, v144
	v_mul_f32_e32 v13, v13, v148
	v_mul_f32_e32 v14, v14, v145
	v_mul_f32_e32 v15, v15, v149
	v_mul_f32_e32 v8, v8, v146
	v_mul_f32_e32 v9, v9, v150
	v_mul_f32_e32 v10, v10, v147
	v_mul_f32_e32 v11, v11, v151
	v_mul_f32_e32 v174, v13, v80
	v_mul_f32_e32 v175, v13, v76
	v_mul_f32_e32 v176, v15, v81
	v_mul_f32_e32 v177, v15, v77
	v_mul_f32_e32 v178, v9, v82
	v_mul_f32_e32 v179, v9, v78
	v_mul_f32_e32 v180, v11, v83
	v_mul_f32_e32 v181, v11, v79
	v_fma_f32 v174, v12, v76, -v174
	v_fma_f32 v175, v12, v80, v175
	v_fma_f32 v176, v14, v77, -v176
	v_fma_f32 v177, v14, v81, v177
	v_fma_f32 v178, v8, v78, -v178
	v_fma_f32 v179, v8, v82, v179
	v_fma_f32 v180, v10, v79, -v180
	v_fma_f32 v181, v10, v83, v181
	v_cvt_pk_bf16_f32 v160, v174, v175
	v_cvt_pk_bf16_f32 v161, v176, v177
	v_cvt_pk_bf16_f32 v162, v178, v179
	v_cvt_pk_bf16_f32 v163, v180, v181
	global_store_dwordx4 v[68:69], v[160:163], off sc1
	v_mul_f32_e32 v4, v4, v198
	v_mul_f32_e32 v5, v5, v198
	v_mul_f32_e32 v6, v6, v198
	v_mul_f32_e32 v7, v7, v198
	v_mul_f32_e32 v0, v0, v198
	v_mul_f32_e32 v1, v1, v198
	v_mul_f32_e32 v2, v2, v198
	v_mul_f32_e32 v3, v3, v198
	v_mul_f32_e32 v4, v4, v144
	v_mul_f32_e32 v5, v5, v148
	v_mul_f32_e32 v6, v6, v145
	v_mul_f32_e32 v7, v7, v149
	v_mul_f32_e32 v0, v0, v146
	v_mul_f32_e32 v1, v1, v150
	v_mul_f32_e32 v2, v2, v147
	v_mul_f32_e32 v3, v3, v151
	v_mul_f32_e32 v174, v5, v80
	v_mul_f32_e32 v175, v5, v76
	v_mul_f32_e32 v176, v7, v81
	v_mul_f32_e32 v177, v7, v77
	v_mul_f32_e32 v178, v1, v82
	v_mul_f32_e32 v179, v1, v78
	v_mul_f32_e32 v180, v3, v83
	v_mul_f32_e32 v181, v3, v79
	v_fma_f32 v174, v4, v76, -v174
	v_fma_f32 v175, v4, v80, v175
	v_fma_f32 v176, v6, v77, -v176
	v_fma_f32 v177, v6, v81, v177
	v_fma_f32 v178, v0, v78, -v178
	v_fma_f32 v179, v0, v82, v179
	v_fma_f32 v180, v2, v79, -v180
	v_fma_f32 v181, v2, v83, v181
	v_cvt_pk_bf16_f32 v182, v174, v175
	v_cvt_pk_bf16_f32 v183, v176, v177
	v_cvt_pk_bf16_f32 v184, v178, v179
	v_cvt_pk_bf16_f32 v185, v180, v181
	global_store_dwordx4 v[68:69], v[182:185], off offset:256 sc1
	s_branch .Lqkv_epi_end
.Lqkv_epi_vrows:
	v_cvt_pk_bf16_f32 v160, v140, v141
	v_cvt_pk_bf16_f32 v161, v142, v143
	v_cvt_pk_bf16_f32 v162, v136, v137
	v_cvt_pk_bf16_f32 v163, v138, v139
	global_store_dwordx4 v[68:69], v[160:163], off sc1
	v_cvt_pk_bf16_f32 v182, v132, v133
	v_cvt_pk_bf16_f32 v183, v134, v135
	v_cvt_pk_bf16_f32 v184, v128, v129
	v_cvt_pk_bf16_f32 v185, v130, v131
	global_store_dwordx4 v[68:69], v[182:185], off offset:256 sc1
	v_cvt_pk_bf16_f32 v160, v124, v125
	v_cvt_pk_bf16_f32 v161, v126, v127
	v_cvt_pk_bf16_f32 v162, v120, v121
	v_cvt_pk_bf16_f32 v163, v122, v123
	v_lshl_add_u64 v[68:69], v[68:69], 0, s[76:77]
	global_store_dwordx4 v[68:69], v[160:163], off sc1
	v_cvt_pk_bf16_f32 v182, v116, v117
	v_cvt_pk_bf16_f32 v183, v118, v119
	v_cvt_pk_bf16_f32 v184, v112, v113
	v_cvt_pk_bf16_f32 v185, v114, v115
	global_store_dwordx4 v[68:69], v[182:185], off offset:256 sc1
	v_cvt_pk_bf16_f32 v160, v108, v109
	v_cvt_pk_bf16_f32 v161, v110, v111
	v_cvt_pk_bf16_f32 v162, v104, v105
	v_cvt_pk_bf16_f32 v163, v106, v107
	v_lshl_add_u64 v[68:69], v[68:69], 0, s[76:77]
	global_store_dwordx4 v[68:69], v[160:163], off sc1
	v_cvt_pk_bf16_f32 v182, v100, v101
	v_cvt_pk_bf16_f32 v183, v102, v103
	v_cvt_pk_bf16_f32 v184, v96, v97
	v_cvt_pk_bf16_f32 v185, v98, v99
	global_store_dwordx4 v[68:69], v[182:185], off offset:256 sc1
	v_cvt_pk_bf16_f32 v160, v92, v93
	v_cvt_pk_bf16_f32 v161, v94, v95
	v_cvt_pk_bf16_f32 v162, v88, v89
	v_cvt_pk_bf16_f32 v163, v90, v91
	v_lshl_add_u64 v[68:69], v[68:69], 0, s[76:77]
	global_store_dwordx4 v[68:69], v[160:163], off sc1
	v_cvt_pk_bf16_f32 v182, v72, v73
	v_cvt_pk_bf16_f32 v183, v74, v75
	v_cvt_pk_bf16_f32 v184, v64, v65
	v_cvt_pk_bf16_f32 v185, v66, v67
	global_store_dwordx4 v[68:69], v[182:185], off offset:256 sc1
	v_cvt_pk_bf16_f32 v160, v60, v61
	v_cvt_pk_bf16_f32 v161, v62, v63
	v_cvt_pk_bf16_f32 v162, v56, v57
	v_cvt_pk_bf16_f32 v163, v58, v59
	v_lshl_add_u64 v[68:69], v[68:69], 0, s[78:79]
	global_store_dwordx4 v[68:69], v[160:163], off sc1
	v_cvt_pk_bf16_f32 v182, v52, v53
	v_cvt_pk_bf16_f32 v183, v54, v55
	v_cvt_pk_bf16_f32 v184, v48, v49
	v_cvt_pk_bf16_f32 v185, v50, v51
	global_store_dwordx4 v[68:69], v[182:185], off offset:256 sc1
	v_cvt_pk_bf16_f32 v160, v44, v45
	v_cvt_pk_bf16_f32 v161, v46, v47
	v_cvt_pk_bf16_f32 v162, v40, v41
	v_cvt_pk_bf16_f32 v163, v42, v43
	v_lshl_add_u64 v[68:69], v[68:69], 0, s[76:77]
	global_store_dwordx4 v[68:69], v[160:163], off sc1
	v_cvt_pk_bf16_f32 v182, v36, v37
	v_cvt_pk_bf16_f32 v183, v38, v39
	v_cvt_pk_bf16_f32 v184, v32, v33
	v_cvt_pk_bf16_f32 v185, v34, v35
	global_store_dwordx4 v[68:69], v[182:185], off offset:256 sc1
	v_cvt_pk_bf16_f32 v160, v28, v29
	v_cvt_pk_bf16_f32 v161, v30, v31
	v_cvt_pk_bf16_f32 v162, v24, v25
	v_cvt_pk_bf16_f32 v163, v26, v27
	v_lshl_add_u64 v[68:69], v[68:69], 0, s[76:77]
	global_store_dwordx4 v[68:69], v[160:163], off sc1
	v_cvt_pk_bf16_f32 v182, v20, v21
	v_cvt_pk_bf16_f32 v183, v22, v23
	v_cvt_pk_bf16_f32 v184, v16, v17
	v_cvt_pk_bf16_f32 v185, v18, v19
	global_store_dwordx4 v[68:69], v[182:185], off offset:256 sc1
	v_cvt_pk_bf16_f32 v160, v12, v13
	v_cvt_pk_bf16_f32 v161, v14, v15
	v_cvt_pk_bf16_f32 v162, v8, v9
	v_cvt_pk_bf16_f32 v163, v10, v11
	v_lshl_add_u64 v[68:69], v[68:69], 0, s[76:77]
	global_store_dwordx4 v[68:69], v[160:163], off sc1
	v_cvt_pk_bf16_f32 v182, v4, v5
	v_cvt_pk_bf16_f32 v183, v6, v7
	v_cvt_pk_bf16_f32 v184, v0, v1
	v_cvt_pk_bf16_f32 v185, v2, v3
	global_store_dwordx4 v[68:69], v[182:185], off offset:256 sc1
.Lqkv_epi_end:
.LBB0_789:
	s_andn2_b64 vcc, exec, s[40:41]
	s_mov_b64 s[40:41], -1
	s_movk_i32 s75, 0x4000
	s_cbranch_vccnz .LBB0_565
	s_andn2_b64 vcc, exec, s[18:19]
	s_cbranch_vccnz .LBB0_564
	s_barrier
	s_branch .LBB0_564
